# plus GU epilogue rewrite (packed silu, paired dwordx4 stores) and q/k bf16 store pairing via permlane16_swap
# speedup vs baseline: 1.0434x; 1.0131x over previous
; template <int EPI>
; __device__ __forceinline__ void gemm_epilogue(KP P, f32x4 (&acc)[2][2][4][2], int brow, int bcol, int wr, int wc, int fr_, int fq_, const float* sRu) {
;     ...
;             if (isq) {
;               uint2 p1, p2;
;               p1.x = cvt_pk_bf16(o1[0] * QSCALE, o1[1] * QSCALE); p1.y = cvt_pk_bf16(o1[2] * QSCALE, o1[3] * QSCALE);
;               p2.x = cvt_pk_bf16(o2[0] * QSCALE, o2[1] * QSCALE); p2.y = cvt_pk_bf16(o2[2] * QSCALE, o2[3] * QSCALE);
;               *(uint2*)(bdst + lr * 1024 + c1) = p1;
;               *(uint2*)(bdst + lr * 1024 + c1 + 32) = p2;
;             } else {
;               *(f32x4*)(fdst + lr * 1024 + c1) = o1;
;               *(f32x4*)(fdst + lr * 1024 + c1 + 32) = o2;
;               unsigned bo;
;               if (prompt) bo = lr * 1024 + c1;
;               else { int rs = row - MP; bo = ((rs >> 6) * SKV + 1024 + (rs & 63)) * 1024 + c1; }
;               uint2 p1, p2;
;               p1.x = cvt_pk_bf16(o1[0], o1[1]); p1.y = cvt_pk_bf16(o1[2], o1[3]);
;               p2.x = cvt_pk_bf16(o2[0], o2[1]); p2.y = cvt_pk_bf16(o2[2], o2[3]);
;               *(uint2*)(bdst + bo) = p1;
;               *(uint2*)(bdst + bo + 32) = p2;
.LBB0_93:
	v_lshl_add_u64 v[2:3], v[0:1], 1, v[14:15]
	v_mov_b64_e32 v[184:185], v[6:7]
	v_mov_b64_e32 v[186:187], v[8:9]
	v_lshl_add_u64 v[192:193], v[2:3], 0, v[232:233]
	s_nop 1
	v_permlane16_swap_b32_e32 v184, v186
	v_permlane16_swap_b32_e32 v185, v187
	global_store_dwordx4 v[192:193], v[184:187], off

; template <int EPI>
; __device__ __forceinline__ void gemm_epilogue(KP P, f32x4 (&acc)[2][2][4][2], int brow, int bcol, int wr, int wc, int fr_, int fq_, const float* sRu) {
;     ...
;     const bool prompt = brow < MP;
;     if (bcol < 2048) {
;       const bool isq = bcol < 1024;
; #pragma unroll
;       for (int bj = 0; bj < 2; ++bj) {
;         const int col32 = bcol + bj * 128 + wc * 32;
;         int frb = fr, fqb = fq;
;         asm volatile("" : "+v"(frb), "+v"(fqb));
;         const unsigned lrow0b = wr * 64 + frb;
;         const int d0 = ((col32 >> 5) & 1) * 16 + fqb * 4;
;         float inv[4];
; #pragma unroll
;         for (int j = 0; j < 4; ++j) inv[j] = exp2f(-(float)(d0 + j) * (13.287712379549449f / 32.f)) * 0.15915494309189535f;
;         const unsigned c1 = (col32 & ~63 & 1023) + d0;
;         bfu* bdst;
;         float* fdst = nullptr;
;         if (isq) bdst = (bfu*)(P->ws + WS_Q) + (size_t)brow * 1024;
;         else if (prompt) { bdst = (bfu*)(P->ws + WS_KP) + (size_t)brow * 1024; fdst = P->out + O_KP + (size_t)brow * 1024; }
;         else { bdst = (bfu*)(P->ws + WS_KSM); fdst = P->out + O_KS + (size_t)(brow - MP) * 1024; }
.LBB0_133:
	s_and_b64 vcc, exec, s[8:9]
	s_cbranch_vccz .LBB0_94
	v_mbcnt_lo_u32_b32 v232, -1, 0
	v_mbcnt_hi_u32_b32 v232, -1, v232
	v_bfe_u32 v232, v232, 4, 1
	v_mul_u32_u24_e32 v232, 56, v232
	v_mov_b32_e32 v233, 0
	s_cmp_gt_i32 s40, 3
	s_cselect_b64 s[44:45], -1, 0
	s_ashr_i32 s5, s4, 31
	s_lshl_b64 s[36:37], s[60:61], 12
	s_lshl_b64 s[34:35], s[4:5], 10
	v_mov_b32_e32 v180, v157
	v_mov_b32_e32 v0, v158
	s_mov_b64 s[38:39], -1
	s_and_b64 vcc, exec, s[44:45]
	s_cbranch_vccz .LBB0_140
	s_and_b64 vcc, exec, s[10:11]
	s_cbranch_vccz .LBB0_137
	s_load_dwordx2 s[8:9], s[0:1], 0xd8
	s_mov_b64 s[38:39], 0
	s_waitcnt lgkmcnt(0)
	s_add_u32 s8, s8, s36
	s_addc_u32 s9, s9, s37
	s_add_u32 s8, s8, 0x31ad8000
	s_addc_u32 s9, s9, 0

; template <int EPI>
; __device__ __forceinline__ void gemm_epilogue(KP P, f32x4 (&acc)[2][2][4][2], int brow, int bcol, int wr, int wc, int fr_, int fq_, const float* sRu) {
;     ...
;             __builtin_amdgcn_sched_barrier(0);
;             unsigned lr = lrow0b + ai * 128 + m * 16;
;             int row = brow + lr;
;             int pos = prompt ? (row & 4095) : 1024 + ((row - MP) & 63);
;             f32x4 x1 = acc[ai][bj][m][0], x2 = acc[ai][bj][m][1], o1, o2;
; #pragma unroll
;             for (int j = 0; j < 4; ++j) {
;               float rev = (float)pos * inv[j];
;               rev -= floorf(rev);
;               float sn = __builtin_amdgcn_sinf(rev), cs = __builtin_amdgcn_cosf(rev);
;               o1[j] = x1[j] * cs - x2[j] * sn;
;               o2[j] = x2[j] * cs + x1[j] * sn;
;             }
;             if (isq) {
;               uint2 p1, p2;
;               p1.x = cvt_pk_bf16(o1[0] * QSCALE, o1[1] * QSCALE); p1.y = cvt_pk_bf16(o1[2] * QSCALE, o1[3] * QSCALE);
;               p2.x = cvt_pk_bf16(o2[0] * QSCALE, o2[1] * QSCALE); p2.y = cvt_pk_bf16(o2[2] * QSCALE, o2[3] * QSCALE);
;               *(uint2*)(bdst + lr * 1024 + c1) = p1;
;               *(uint2*)(bdst + lr * 1024 + c1 + 32) = p2;
;             } else {
;               *(f32x4*)(fdst + lr * 1024 + c1) = o1;
;               *(f32x4*)(fdst + lr * 1024 + c1 + 32) = o2;
;               unsigned bo;
;               if (prompt) bo = lr * 1024 + c1;
;               else { int rs = row - MP; bo = ((rs >> 6) * SKV + 1024 + (rs & 63)) * 1024 + c1; }
;               uint2 p1, p2;
;               p1.x = cvt_pk_bf16(o1[0], o1[1]); p1.y = cvt_pk_bf16(o1[2], o1[3]);
;               p2.x = cvt_pk_bf16(o2[0], o2[1]); p2.y = cvt_pk_bf16(o2[2], o2[3]);
;               *(uint2*)(bdst + bo) = p1;
;               *(uint2*)(bdst + bo + 32) = p2;
.LBB0_148:
	v_add_u32_e32 v122, 16, v180
	v_mov_b32_e32 v151, v1
	v_and_b32_e32 v132, 63, v122
	v_lshl_add_u64 v[122:123], v[150:151], 1, v[152:153]
	v_mov_b64_e32 v[188:189], v[128:129]
	v_mov_b64_e32 v[190:191], v[144:145]
	v_lshl_add_u64 v[194:195], v[122:123], 0, v[232:233]
	s_nop 1
	v_permlane16_swap_b32_e32 v188, v190
	v_permlane16_swap_b32_e32 v189, v191
	global_store_dwordx4 v[194:195], v[188:191], off
	v_add_u32_e32 v130, 16, v163
	v_add_u32_e32 v129, s4, v130
	v_and_b32_e32 v122, 0xfff, v129
	v_or_b32_e32 v133, 0x400, v132
	v_cndmask_b32_e64 v122, v133, v122, s[6:7]
	v_cvt_f32_u32_e32 v128, v122
	s_mov_b64 s[42:43], -1
	s_andn2_b64 vcc, exec, s[44:45]
	v_mul_f32_e32 v122, v159, v128
	v_floor_f32_e32 v122, v122
	v_fma_f32 v122, v159, v128, -v122
	v_sin_f32_e32 v124, v122
	v_cos_f32_e32 v144, v122
	v_mul_f32_e32 v122, v160, v128
	v_floor_f32_e32 v122, v122
	v_fma_f32 v122, v160, v128, -v122
	v_sin_f32_e32 v125, v122
	v_cos_f32_e32 v145, v122
	v_pk_mul_f32 v[122:123], v[114:115], v[124:125]
	v_pk_mul_f32 v[114:115], v[114:115], v[144:145]
	v_pk_fma_f32 v[122:123], v[118:119], v[144:145], v[122:123] neg_lo:[0,0,1] neg_hi:[0,0,1]
	v_pk_fma_f32 v[114:115], v[118:119], v[124:125], v[114:115]
	v_mul_f32_e32 v118, v161, v128
	v_floor_f32_e32 v118, v118
	v_fma_f32 v119, v161, v128, -v118
	v_sin_f32_e32 v118, v119
	v_cos_f32_e32 v144, v119
	v_mul_f32_e32 v119, v162, v128
	v_floor_f32_e32 v119, v119
	v_fma_f32 v124, v162, v128, -v119
	v_sin_f32_e32 v119, v124
	v_cos_f32_e32 v145, v124
	v_pk_mul_f32 v[124:125], v[116:117], v[118:119]
	v_pk_mul_f32 v[116:117], v[116:117], v[144:145]
	v_pk_fma_f32 v[124:125], v[120:121], v[144:145], v[124:125] neg_lo:[0,0,1] neg_hi:[0,0,1]
	v_pk_fma_f32 v[116:117], v[120:121], v[118:119], v[116:117]
	v_cndmask_b32_e64 v118, 0, 1, s[44:45]
	v_cmp_ne_u32_e64 s[10:11], 1, v118
	v_lshlrev_b32_e32 v144, 10, v130
	s_cbranch_vccnz .LBB0_152
	v_lshlrev_b32_e32 v118, 10, v130
	v_mov_b32_e32 v119, v1
	v_lshl_add_u64 v[120:121], v[118:119], 2, v[142:143]
	s_and_b64 vcc, exec, s[8:9]
	global_store_dwordx4 v[120:121], v[122:125], off
	global_store_dwordx4 v[120:121], v[114:117], off offset:128
	s_cbranch_vccnz .LBB0_151
	v_add_u32_e32 v118, 0xffff0000, v129
	v_lshrrev_b32_e32 v118, 6, v118
	v_mul_lo_u32 v118, v118, s57
	v_or_b32_e32 v118, v118, v132
	v_lshl_add_u32 v118, v118, 10, v170

; template <int EPI>
; __device__ __forceinline__ void gemm_epilogue(KP P, f32x4 (&acc)[2][2][4][2], int brow, int bcol, int wr, int wc, int fr_, int fq_, const float* sRu) {
;     ...
;             __builtin_amdgcn_sched_barrier(0);
;             unsigned lr = lrow0b + ai * 128 + m * 16;
;             int row = brow + lr;
;             int pos = prompt ? (row & 4095) : 1024 + ((row - MP) & 63);
;             f32x4 x1 = acc[ai][bj][m][0], x2 = acc[ai][bj][m][1], o1, o2;
; #pragma unroll
;             for (int j = 0; j < 4; ++j) {
;               float rev = (float)pos * inv[j];
;               rev -= floorf(rev);
;               float sn = __builtin_amdgcn_sinf(rev), cs = __builtin_amdgcn_cosf(rev);
;               o1[j] = x1[j] * cs - x2[j] * sn;
;               o2[j] = x2[j] * cs + x1[j] * sn;
;             }
;             if (isq) {
;               uint2 p1, p2;
;               p1.x = cvt_pk_bf16(o1[0] * QSCALE, o1[1] * QSCALE); p1.y = cvt_pk_bf16(o1[2] * QSCALE, o1[3] * QSCALE);
;               p2.x = cvt_pk_bf16(o2[0] * QSCALE, o2[1] * QSCALE); p2.y = cvt_pk_bf16(o2[2] * QSCALE, o2[3] * QSCALE);
;               *(uint2*)(bdst + lr * 1024 + c1) = p1;
;               *(uint2*)(bdst + lr * 1024 + c1 + 32) = p2;
;             } else {
;               *(f32x4*)(fdst + lr * 1024 + c1) = o1;
;               *(f32x4*)(fdst + lr * 1024 + c1 + 32) = o2;
;               unsigned bo;
;               if (prompt) bo = lr * 1024 + c1;
;               else { int rs = row - MP; bo = ((rs >> 6) * SKV + 1024 + (rs & 63)) * 1024 + c1; }
;               uint2 p1, p2;
;               p1.x = cvt_pk_bf16(o1[0], o1[1]); p1.y = cvt_pk_bf16(o1[2], o1[3]);
;               p2.x = cvt_pk_bf16(o2[0], o2[1]); p2.y = cvt_pk_bf16(o2[2], o2[3]);
;               *(uint2*)(bdst + bo) = p1;
;               *(uint2*)(bdst + bo + 32) = p2;
.LBB0_154:
	v_mov_b32_e32 v129, v1
	v_xor_b32_e32 v122, 32, v179
	v_lshl_add_u64 v[114:115], v[128:129], 1, v[130:131]
	v_mov_b64_e32 v[184:185], v[118:119]
	v_mov_b64_e32 v[186:187], v[120:121]
	v_lshl_add_u64 v[192:193], v[114:115], 0, v[232:233]
	s_nop 1
	v_permlane16_swap_b32_e32 v184, v186
	v_permlane16_swap_b32_e32 v185, v187
	global_store_dwordx4 v[192:193], v[184:187], off
	v_add_u32_e32 v120, 32, v163
	v_add_u32_e32 v119, s4, v120
	s_movk_i32 s25, 0x400
	v_and_b32_e32 v114, 0xfff, v119
	v_bitop3_b32 v123, v179, s25, 32 bitop3:0xde
	v_cndmask_b32_e64 v114, v123, v114, s[6:7]
	v_cvt_f32_u32_e32 v118, v114
	s_mov_b64 s[42:43], -1
	s_and_b64 vcc, exec, s[10:11]
	v_mul_f32_e32 v114, v159, v118
	v_floor_f32_e32 v114, v114
	v_fma_f32 v114, v159, v118, -v114
	v_sin_f32_e32 v116, v114
	v_cos_f32_e32 v124, v114
	v_mul_f32_e32 v114, v160, v118
	v_floor_f32_e32 v114, v114
	v_fma_f32 v114, v160, v118, -v114
	v_sin_f32_e32 v117, v114
	v_cos_f32_e32 v125, v114
	v_pk_mul_f32 v[114:115], v[106:107], v[116:117]
	v_pk_mul_f32 v[106:107], v[106:107], v[124:125]
	v_pk_fma_f32 v[114:115], v[110:111], v[124:125], v[114:115] neg_lo:[0,0,1] neg_hi:[0,0,1]
	v_pk_fma_f32 v[106:107], v[110:111], v[116:117], v[106:107]
	v_mul_f32_e32 v110, v161, v118
	v_floor_f32_e32 v110, v110
	v_fma_f32 v111, v161, v118, -v110
	v_sin_f32_e32 v110, v111
	v_cos_f32_e32 v124, v111
	v_mul_f32_e32 v111, v162, v118
	v_floor_f32_e32 v111, v111
	v_fma_f32 v116, v162, v118, -v111
	v_sin_f32_e32 v111, v116
	v_cos_f32_e32 v125, v116
	v_pk_mul_f32 v[116:117], v[108:109], v[110:111]
	v_pk_mul_f32 v[108:109], v[108:109], v[124:125]
	v_pk_fma_f32 v[116:117], v[112:113], v[124:125], v[116:117] neg_lo:[0,0,1] neg_hi:[0,0,1]
	v_pk_fma_f32 v[108:109], v[112:113], v[110:111], v[108:109]
	v_lshlrev_b32_e32 v124, 10, v120
	s_cbranch_vccnz .LBB0_158
	v_lshlrev_b32_e32 v110, 10, v120
	v_mov_b32_e32 v111, v1
	v_lshl_add_u64 v[112:113], v[110:111], 2, v[142:143]
	s_and_b64 vcc, exec, s[8:9]
	global_store_dwordx4 v[112:113], v[114:117], off
	global_store_dwordx4 v[112:113], v[106:109], off offset:128
	s_cbranch_vccnz .LBB0_157
	v_add_u32_e32 v110, 0xffff0000, v119
	v_lshrrev_b32_e32 v110, 6, v110
	v_mul_lo_u32 v110, v110, s57
	v_or_b32_e32 v110, v110, v122
	v_lshl_add_u32 v110, v110, 10, v170

; template <int EPI>
; __device__ __forceinline__ void gemm_epilogue(KP P, f32x4 (&acc)[2][2][4][2], int brow, int bcol, int wr, int wc, int fr_, int fq_, const float* sRu) {
;     ...
;             __builtin_amdgcn_sched_barrier(0);
;             unsigned lr = lrow0b + ai * 128 + m * 16;
;             int row = brow + lr;
;             int pos = prompt ? (row & 4095) : 1024 + ((row - MP) & 63);
;             f32x4 x1 = acc[ai][bj][m][0], x2 = acc[ai][bj][m][1], o1, o2;
; #pragma unroll
;             for (int j = 0; j < 4; ++j) {
;               float rev = (float)pos * inv[j];
;               rev -= floorf(rev);
;               float sn = __builtin_amdgcn_sinf(rev), cs = __builtin_amdgcn_cosf(rev);
;               o1[j] = x1[j] * cs - x2[j] * sn;
;               o2[j] = x2[j] * cs + x1[j] * sn;
;             }
;             if (isq) {
;               uint2 p1, p2;
;               p1.x = cvt_pk_bf16(o1[0] * QSCALE, o1[1] * QSCALE); p1.y = cvt_pk_bf16(o1[2] * QSCALE, o1[3] * QSCALE);
;               p2.x = cvt_pk_bf16(o2[0] * QSCALE, o2[1] * QSCALE); p2.y = cvt_pk_bf16(o2[2] * QSCALE, o2[3] * QSCALE);
;               *(uint2*)(bdst + lr * 1024 + c1) = p1;
;               *(uint2*)(bdst + lr * 1024 + c1 + 32) = p2;
;             } else {
;               *(f32x4*)(fdst + lr * 1024 + c1) = o1;
;               *(f32x4*)(fdst + lr * 1024 + c1 + 32) = o2;
;               unsigned bo;
;               if (prompt) bo = lr * 1024 + c1;
;               else { int rs = row - MP; bo = ((rs >> 6) * SKV + 1024 + (rs & 63)) * 1024 + c1; }
;               uint2 p1, p2;
;               p1.x = cvt_pk_bf16(o1[0], o1[1]); p1.y = cvt_pk_bf16(o1[2], o1[3]);
;               p2.x = cvt_pk_bf16(o2[0], o2[1]); p2.y = cvt_pk_bf16(o2[2], o2[3]);
;               *(uint2*)(bdst + bo) = p1;
;               *(uint2*)(bdst + bo + 32) = p2;
.LBB0_160:
	v_add_u32_e32 v106, 48, v180
	v_mov_b32_e32 v119, v1
	v_and_b32_e32 v114, 63, v106
	v_lshl_add_u64 v[106:107], v[118:119], 1, v[120:121]
	v_mov_b64_e32 v[188:189], v[110:111]
	v_mov_b64_e32 v[190:191], v[112:113]
	v_lshl_add_u64 v[194:195], v[106:107], 0, v[232:233]
	s_nop 1
	v_permlane16_swap_b32_e32 v188, v190
	v_permlane16_swap_b32_e32 v189, v191
	global_store_dwordx4 v[194:195], v[188:191], off
	v_add_u32_e32 v112, 48, v163
	v_add_u32_e32 v111, s4, v112
	v_and_b32_e32 v106, 0xfff, v111
	v_or_b32_e32 v115, 0x400, v114
	v_cndmask_b32_e64 v106, v115, v106, s[6:7]
	v_cvt_f32_u32_e32 v110, v106
	s_mov_b64 s[42:43], -1
	s_and_b64 vcc, exec, s[10:11]
	v_mul_f32_e32 v106, v159, v110
	v_floor_f32_e32 v106, v106
	v_fma_f32 v106, v159, v110, -v106
	v_sin_f32_e32 v108, v106
	v_cos_f32_e32 v116, v106
	v_mul_f32_e32 v106, v160, v110
	v_floor_f32_e32 v106, v106
	v_fma_f32 v106, v160, v110, -v106
	v_sin_f32_e32 v109, v106
	v_cos_f32_e32 v117, v106
	v_pk_mul_f32 v[106:107], v[98:99], v[108:109]
	v_pk_mul_f32 v[98:99], v[98:99], v[116:117]
	v_pk_fma_f32 v[106:107], v[102:103], v[116:117], v[106:107] neg_lo:[0,0,1] neg_hi:[0,0,1]
	v_pk_fma_f32 v[98:99], v[102:103], v[108:109], v[98:99]
	v_mul_f32_e32 v102, v161, v110
	v_floor_f32_e32 v102, v102
	v_fma_f32 v103, v161, v110, -v102
	v_sin_f32_e32 v102, v103
	v_cos_f32_e32 v116, v103
	v_mul_f32_e32 v103, v162, v110
	v_floor_f32_e32 v103, v103
	v_fma_f32 v108, v162, v110, -v103
	v_sin_f32_e32 v103, v108
	v_cos_f32_e32 v117, v108
	v_pk_mul_f32 v[108:109], v[100:101], v[102:103]
	v_pk_mul_f32 v[100:101], v[100:101], v[116:117]
	v_pk_fma_f32 v[108:109], v[104:105], v[116:117], v[108:109] neg_lo:[0,0,1] neg_hi:[0,0,1]
	v_pk_fma_f32 v[100:101], v[104:105], v[102:103], v[100:101]
	v_lshlrev_b32_e32 v116, 10, v112
	s_cbranch_vccnz .LBB0_164
	v_lshlrev_b32_e32 v102, 10, v112
	v_mov_b32_e32 v103, v1
	v_lshl_add_u64 v[104:105], v[102:103], 2, v[142:143]
	s_and_b64 vcc, exec, s[8:9]
	global_store_dwordx4 v[104:105], v[106:109], off
	global_store_dwordx4 v[104:105], v[98:101], off offset:128
	s_cbranch_vccnz .LBB0_163
	v_add_u32_e32 v102, 0xffff0000, v111
	v_lshrrev_b32_e32 v102, 6, v102
	v_mul_lo_u32 v102, v102, s57
	v_or_b32_e32 v102, v102, v114
	v_lshl_add_u32 v102, v102, 10, v170

; template <int EPI>
; __device__ __forceinline__ void gemm_epilogue(KP P, f32x4 (&acc)[2][2][4][2], int brow, int bcol, int wr, int wc, int fr_, int fq_, const float* sRu) {
;     ...
;             __builtin_amdgcn_sched_barrier(0);
;             unsigned lr = lrow0b + ai * 128 + m * 16;
;             int row = brow + lr;
;             int pos = prompt ? (row & 4095) : 1024 + ((row - MP) & 63);
;             f32x4 x1 = acc[ai][bj][m][0], x2 = acc[ai][bj][m][1], o1, o2;
; #pragma unroll
;             for (int j = 0; j < 4; ++j) {
;               float rev = (float)pos * inv[j];
;               rev -= floorf(rev);
;               float sn = __builtin_amdgcn_sinf(rev), cs = __builtin_amdgcn_cosf(rev);
;               o1[j] = x1[j] * cs - x2[j] * sn;
;               o2[j] = x2[j] * cs + x1[j] * sn;
;             }
;             if (isq) {
;               uint2 p1, p2;
;               p1.x = cvt_pk_bf16(o1[0] * QSCALE, o1[1] * QSCALE); p1.y = cvt_pk_bf16(o1[2] * QSCALE, o1[3] * QSCALE);
;               p2.x = cvt_pk_bf16(o2[0] * QSCALE, o2[1] * QSCALE); p2.y = cvt_pk_bf16(o2[2] * QSCALE, o2[3] * QSCALE);
;               *(uint2*)(bdst + lr * 1024 + c1) = p1;
;               *(uint2*)(bdst + lr * 1024 + c1 + 32) = p2;
;             } else {
;               *(f32x4*)(fdst + lr * 1024 + c1) = o1;
;               *(f32x4*)(fdst + lr * 1024 + c1 + 32) = o2;
;               unsigned bo;
;               if (prompt) bo = lr * 1024 + c1;
;               else { int rs = row - MP; bo = ((rs >> 6) * SKV + 1024 + (rs & 63)) * 1024 + c1; }
;               uint2 p1, p2;
;               p1.x = cvt_pk_bf16(o1[0], o1[1]); p1.y = cvt_pk_bf16(o1[2], o1[3]);
;               p2.x = cvt_pk_bf16(o2[0], o2[1]); p2.y = cvt_pk_bf16(o2[2], o2[3]);
;               *(uint2*)(bdst + bo) = p1;
;               *(uint2*)(bdst + bo + 32) = p2;
.LBB0_166:
	v_mov_b32_e32 v111, v1
	v_lshl_add_u64 v[98:99], v[110:111], 1, v[112:113]
	v_mov_b64_e32 v[184:185], v[102:103]
	v_mov_b64_e32 v[186:187], v[104:105]
	v_lshl_add_u64 v[192:193], v[98:99], 0, v[232:233]
	s_nop 1
	v_permlane16_swap_b32_e32 v184, v186
	v_permlane16_swap_b32_e32 v185, v187
	global_store_dwordx4 v[192:193], v[184:187], off
	v_add_u32_e32 v104, 0x80, v163
	v_add_u32_e32 v103, s4, v104
	v_and_b32_e32 v98, 0xfff, v103
	v_cndmask_b32_e64 v98, v181, v98, s[6:7]
	v_cvt_f32_u32_e32 v102, v98
	s_mov_b64 s[42:43], -1
	s_and_b64 vcc, exec, s[10:11]
	v_mul_f32_e32 v98, v159, v102
	v_floor_f32_e32 v98, v98
	v_fma_f32 v98, v159, v102, -v98
	v_sin_f32_e32 v100, v98
	v_cos_f32_e32 v106, v98
	v_mul_f32_e32 v98, v160, v102
	v_floor_f32_e32 v98, v98
	v_fma_f32 v98, v160, v102, -v98
	v_sin_f32_e32 v101, v98
	v_cos_f32_e32 v107, v98
	v_pk_mul_f32 v[98:99], v[90:91], v[100:101]
	v_pk_mul_f32 v[90:91], v[90:91], v[106:107]
	v_pk_fma_f32 v[98:99], v[94:95], v[106:107], v[98:99] neg_lo:[0,0,1] neg_hi:[0,0,1]
	v_pk_fma_f32 v[90:91], v[94:95], v[100:101], v[90:91]
	v_mul_f32_e32 v94, v161, v102
	v_floor_f32_e32 v94, v94
	v_fma_f32 v95, v161, v102, -v94
	v_sin_f32_e32 v94, v95
	v_cos_f32_e32 v106, v95
	v_mul_f32_e32 v95, v162, v102
	v_floor_f32_e32 v95, v95
	v_fma_f32 v100, v162, v102, -v95
	v_sin_f32_e32 v95, v100
	v_cos_f32_e32 v107, v100
	v_pk_mul_f32 v[100:101], v[92:93], v[94:95]
	v_pk_mul_f32 v[92:93], v[92:93], v[106:107]
	v_pk_fma_f32 v[100:101], v[96:97], v[106:107], v[100:101] neg_lo:[0,0,1] neg_hi:[0,0,1]
	v_pk_fma_f32 v[92:93], v[96:97], v[94:95], v[92:93]
	v_lshlrev_b32_e32 v106, 10, v104
	s_cbranch_vccnz .LBB0_170
	v_lshlrev_b32_e32 v94, 10, v104
	v_mov_b32_e32 v95, v1
	v_lshl_add_u64 v[96:97], v[94:95], 2, v[142:143]
	s_and_b64 vcc, exec, s[8:9]
	global_store_dwordx4 v[96:97], v[98:101], off
	global_store_dwordx4 v[96:97], v[90:93], off offset:128
	s_cbranch_vccnz .LBB0_169
	v_add_u32_e32 v94, 0xffff0000, v103
	v_lshrrev_b32_e32 v94, 6, v94
	v_mul_lo_u32 v94, v94, s57
	v_or_b32_e32 v94, v94, v179
	v_lshl_add_u32 v94, v94, 10, v170

; template <int EPI>
; __device__ __forceinline__ void gemm_epilogue(KP P, f32x4 (&acc)[2][2][4][2], int brow, int bcol, int wr, int wc, int fr_, int fq_, const float* sRu) {
;     ...
;             __builtin_amdgcn_sched_barrier(0);
;             unsigned lr = lrow0b + ai * 128 + m * 16;
;             int row = brow + lr;
;             int pos = prompt ? (row & 4095) : 1024 + ((row - MP) & 63);
;             f32x4 x1 = acc[ai][bj][m][0], x2 = acc[ai][bj][m][1], o1, o2;
; #pragma unroll
;             for (int j = 0; j < 4; ++j) {
;               float rev = (float)pos * inv[j];
;               rev -= floorf(rev);
;               float sn = __builtin_amdgcn_sinf(rev), cs = __builtin_amdgcn_cosf(rev);
;               o1[j] = x1[j] * cs - x2[j] * sn;
;               o2[j] = x2[j] * cs + x1[j] * sn;
;             }
;             if (isq) {
;               uint2 p1, p2;
;               p1.x = cvt_pk_bf16(o1[0] * QSCALE, o1[1] * QSCALE); p1.y = cvt_pk_bf16(o1[2] * QSCALE, o1[3] * QSCALE);
;               p2.x = cvt_pk_bf16(o2[0] * QSCALE, o2[1] * QSCALE); p2.y = cvt_pk_bf16(o2[2] * QSCALE, o2[3] * QSCALE);
;               *(uint2*)(bdst + lr * 1024 + c1) = p1;
;               *(uint2*)(bdst + lr * 1024 + c1 + 32) = p2;
;             } else {
;               *(f32x4*)(fdst + lr * 1024 + c1) = o1;
;               *(f32x4*)(fdst + lr * 1024 + c1 + 32) = o2;
;               unsigned bo;
;               if (prompt) bo = lr * 1024 + c1;
;               else { int rs = row - MP; bo = ((rs >> 6) * SKV + 1024 + (rs & 63)) * 1024 + c1; }
;               uint2 p1, p2;
;               p1.x = cvt_pk_bf16(o1[0], o1[1]); p1.y = cvt_pk_bf16(o1[2], o1[3]);
;               p2.x = cvt_pk_bf16(o2[0], o2[1]); p2.y = cvt_pk_bf16(o2[2], o2[3]);
;               *(uint2*)(bdst + bo) = p1;
;               *(uint2*)(bdst + bo + 32) = p2;
.LBB0_172:
	v_mov_b32_e32 v103, v1
	v_lshl_add_u64 v[90:91], v[102:103], 1, v[104:105]
	v_mov_b64_e32 v[188:189], v[94:95]
	v_mov_b64_e32 v[190:191], v[96:97]
	v_lshl_add_u64 v[194:195], v[90:91], 0, v[232:233]
	s_nop 1
	v_permlane16_swap_b32_e32 v188, v190
	v_permlane16_swap_b32_e32 v189, v191
	global_store_dwordx4 v[194:195], v[188:191], off
	v_add_u32_e32 v96, 0x90, v163
	v_add_u32_e32 v95, s4, v96
	v_and_b32_e32 v90, 0xfff, v95
	v_cndmask_b32_e64 v90, v133, v90, s[6:7]
	v_cvt_f32_u32_e32 v94, v90
	s_mov_b64 s[42:43], -1
	s_and_b64 vcc, exec, s[10:11]
	v_mul_f32_e32 v90, v159, v94
	v_floor_f32_e32 v90, v90
	v_fma_f32 v90, v159, v94, -v90
	v_sin_f32_e32 v92, v90
	v_cos_f32_e32 v98, v90
	v_mul_f32_e32 v90, v160, v94
	v_floor_f32_e32 v90, v90
	v_fma_f32 v90, v160, v94, -v90
	v_sin_f32_e32 v93, v90
	v_cos_f32_e32 v99, v90
	v_pk_mul_f32 v[90:91], v[82:83], v[92:93]
	v_pk_mul_f32 v[82:83], v[82:83], v[98:99]
	v_pk_fma_f32 v[90:91], v[86:87], v[98:99], v[90:91] neg_lo:[0,0,1] neg_hi:[0,0,1]
	v_pk_fma_f32 v[82:83], v[86:87], v[92:93], v[82:83]
	v_mul_f32_e32 v86, v161, v94
	v_floor_f32_e32 v86, v86
	v_fma_f32 v87, v161, v94, -v86
	v_sin_f32_e32 v86, v87
	v_cos_f32_e32 v98, v87
	v_mul_f32_e32 v87, v162, v94
	v_floor_f32_e32 v87, v87
	v_fma_f32 v92, v162, v94, -v87
	v_sin_f32_e32 v87, v92
	v_cos_f32_e32 v99, v92
	v_pk_mul_f32 v[92:93], v[84:85], v[86:87]
	v_pk_mul_f32 v[84:85], v[84:85], v[98:99]
	v_pk_fma_f32 v[92:93], v[88:89], v[98:99], v[92:93] neg_lo:[0,0,1] neg_hi:[0,0,1]
	v_pk_fma_f32 v[84:85], v[88:89], v[86:87], v[84:85]
	v_lshlrev_b32_e32 v98, 10, v96
	s_cbranch_vccnz .LBB0_176
	v_lshlrev_b32_e32 v86, 10, v96
	v_mov_b32_e32 v87, v1
	v_lshl_add_u64 v[88:89], v[86:87], 2, v[142:143]
	s_and_b64 vcc, exec, s[8:9]
	global_store_dwordx4 v[88:89], v[90:93], off
	global_store_dwordx4 v[88:89], v[82:85], off offset:128
	s_cbranch_vccnz .LBB0_175
	v_add_u32_e32 v86, 0xffff0000, v95
	v_lshrrev_b32_e32 v86, 6, v86
	v_mul_lo_u32 v86, v86, s57
	v_or_b32_e32 v86, v86, v132
	v_lshl_add_u32 v86, v86, 10, v170

; template <int EPI>
; __device__ __forceinline__ void gemm_epilogue(KP P, f32x4 (&acc)[2][2][4][2], int brow, int bcol, int wr, int wc, int fr_, int fq_, const float* sRu) {
;     ...
;             __builtin_amdgcn_sched_barrier(0);
;             unsigned lr = lrow0b + ai * 128 + m * 16;
;             int row = brow + lr;
;             int pos = prompt ? (row & 4095) : 1024 + ((row - MP) & 63);
;             f32x4 x1 = acc[ai][bj][m][0], x2 = acc[ai][bj][m][1], o1, o2;
; #pragma unroll
;             for (int j = 0; j < 4; ++j) {
;               float rev = (float)pos * inv[j];
;               rev -= floorf(rev);
;               float sn = __builtin_amdgcn_sinf(rev), cs = __builtin_amdgcn_cosf(rev);
;               o1[j] = x1[j] * cs - x2[j] * sn;
;               o2[j] = x2[j] * cs + x1[j] * sn;
;             }
;             if (isq) {
;               uint2 p1, p2;
;               p1.x = cvt_pk_bf16(o1[0] * QSCALE, o1[1] * QSCALE); p1.y = cvt_pk_bf16(o1[2] * QSCALE, o1[3] * QSCALE);
;               p2.x = cvt_pk_bf16(o2[0] * QSCALE, o2[1] * QSCALE); p2.y = cvt_pk_bf16(o2[2] * QSCALE, o2[3] * QSCALE);
;               *(uint2*)(bdst + lr * 1024 + c1) = p1;
;               *(uint2*)(bdst + lr * 1024 + c1 + 32) = p2;
;             } else {
;               *(f32x4*)(fdst + lr * 1024 + c1) = o1;
;               *(f32x4*)(fdst + lr * 1024 + c1 + 32) = o2;
;               unsigned bo;
;               if (prompt) bo = lr * 1024 + c1;
;               else { int rs = row - MP; bo = ((rs >> 6) * SKV + 1024 + (rs & 63)) * 1024 + c1; }
;               uint2 p1, p2;
;               p1.x = cvt_pk_bf16(o1[0], o1[1]); p1.y = cvt_pk_bf16(o1[2], o1[3]);
;               p2.x = cvt_pk_bf16(o2[0], o2[1]); p2.y = cvt_pk_bf16(o2[2], o2[3]);
;               *(uint2*)(bdst + bo) = p1;
;               *(uint2*)(bdst + bo + 32) = p2;
.LBB0_178:
	v_mov_b32_e32 v95, v1
	v_lshl_add_u64 v[82:83], v[94:95], 1, v[96:97]
	v_mov_b64_e32 v[184:185], v[86:87]
	v_mov_b64_e32 v[186:187], v[88:89]
	v_lshl_add_u64 v[192:193], v[82:83], 0, v[232:233]
	s_nop 1
	v_permlane16_swap_b32_e32 v184, v186
	v_permlane16_swap_b32_e32 v185, v187
	global_store_dwordx4 v[192:193], v[184:187], off
	v_add_u32_e32 v88, 0xa0, v163
	v_add_u32_e32 v87, s4, v88
	v_and_b32_e32 v82, 0xfff, v87
	v_cndmask_b32_e64 v82, v123, v82, s[6:7]
	v_cvt_f32_u32_e32 v86, v82
	s_mov_b64 s[42:43], -1
	s_and_b64 vcc, exec, s[10:11]
	v_mul_f32_e32 v82, v159, v86
	v_floor_f32_e32 v82, v82
	v_fma_f32 v82, v159, v86, -v82
	v_sin_f32_e32 v84, v82
	v_cos_f32_e32 v90, v82
	v_mul_f32_e32 v82, v160, v86
	v_floor_f32_e32 v82, v82
	v_fma_f32 v82, v160, v86, -v82
	v_sin_f32_e32 v85, v82
	v_cos_f32_e32 v91, v82
	v_pk_mul_f32 v[82:83], v[74:75], v[84:85]
	v_pk_mul_f32 v[74:75], v[74:75], v[90:91]
	v_pk_fma_f32 v[82:83], v[78:79], v[90:91], v[82:83] neg_lo:[0,0,1] neg_hi:[0,0,1]
	v_pk_fma_f32 v[74:75], v[78:79], v[84:85], v[74:75]
	v_mul_f32_e32 v78, v161, v86
	v_floor_f32_e32 v78, v78
	v_fma_f32 v79, v161, v86, -v78
	v_sin_f32_e32 v78, v79
	v_cos_f32_e32 v90, v79
	v_mul_f32_e32 v79, v162, v86
	v_floor_f32_e32 v79, v79
	v_fma_f32 v84, v162, v86, -v79
	v_sin_f32_e32 v79, v84
	v_cos_f32_e32 v91, v84
	v_pk_mul_f32 v[84:85], v[76:77], v[78:79]
	v_pk_mul_f32 v[76:77], v[76:77], v[90:91]
	v_pk_fma_f32 v[84:85], v[80:81], v[90:91], v[84:85] neg_lo:[0,0,1] neg_hi:[0,0,1]
	v_pk_fma_f32 v[76:77], v[80:81], v[78:79], v[76:77]
	v_lshlrev_b32_e32 v90, 10, v88
	s_cbranch_vccnz .LBB0_182
	v_lshlrev_b32_e32 v78, 10, v88
	v_mov_b32_e32 v79, v1
	v_lshl_add_u64 v[80:81], v[78:79], 2, v[142:143]
	s_and_b64 vcc, exec, s[8:9]
	global_store_dwordx4 v[80:81], v[82:85], off
	global_store_dwordx4 v[80:81], v[74:77], off offset:128
	s_cbranch_vccnz .LBB0_181
	v_add_u32_e32 v78, 0xffff0000, v87
	v_lshrrev_b32_e32 v78, 6, v78
	v_mul_lo_u32 v78, v78, s57
	v_or_b32_e32 v78, v78, v122
	v_lshl_add_u32 v78, v78, 10, v170

; template <int EPI>
; __device__ __forceinline__ void gemm_epilogue(KP P, f32x4 (&acc)[2][2][4][2], int brow, int bcol, int wr, int wc, int fr_, int fq_, const float* sRu) {
;     ...
;             __builtin_amdgcn_sched_barrier(0);
;             unsigned lr = lrow0b + ai * 128 + m * 16;
;             int row = brow + lr;
;             int pos = prompt ? (row & 4095) : 1024 + ((row - MP) & 63);
;             f32x4 x1 = acc[ai][bj][m][0], x2 = acc[ai][bj][m][1], o1, o2;
; #pragma unroll
;             for (int j = 0; j < 4; ++j) {
;               float rev = (float)pos * inv[j];
;               rev -= floorf(rev);
;               float sn = __builtin_amdgcn_sinf(rev), cs = __builtin_amdgcn_cosf(rev);
;               o1[j] = x1[j] * cs - x2[j] * sn;
;               o2[j] = x2[j] * cs + x1[j] * sn;
;             }
;             if (isq) {
;               uint2 p1, p2;
;               p1.x = cvt_pk_bf16(o1[0] * QSCALE, o1[1] * QSCALE); p1.y = cvt_pk_bf16(o1[2] * QSCALE, o1[3] * QSCALE);
;               p2.x = cvt_pk_bf16(o2[0] * QSCALE, o2[1] * QSCALE); p2.y = cvt_pk_bf16(o2[2] * QSCALE, o2[3] * QSCALE);
;               *(uint2*)(bdst + lr * 1024 + c1) = p1;
;               *(uint2*)(bdst + lr * 1024 + c1 + 32) = p2;
;             } else {
;               *(f32x4*)(fdst + lr * 1024 + c1) = o1;
;               *(f32x4*)(fdst + lr * 1024 + c1 + 32) = o2;
;               unsigned bo;
;               if (prompt) bo = lr * 1024 + c1;
;               else { int rs = row - MP; bo = ((rs >> 6) * SKV + 1024 + (rs & 63)) * 1024 + c1; }
;               uint2 p1, p2;
;               p1.x = cvt_pk_bf16(o1[0], o1[1]); p1.y = cvt_pk_bf16(o1[2], o1[3]);
;               p2.x = cvt_pk_bf16(o2[0], o2[1]); p2.y = cvt_pk_bf16(o2[2], o2[3]);
;               *(uint2*)(bdst + bo) = p1;
;               *(uint2*)(bdst + bo + 32) = p2;
.LBB0_184:
	v_mov_b32_e32 v87, v1
	v_lshl_add_u64 v[74:75], v[86:87], 1, v[88:89]
	v_mov_b64_e32 v[188:189], v[78:79]
	v_mov_b64_e32 v[190:191], v[80:81]
	v_lshl_add_u64 v[194:195], v[74:75], 0, v[232:233]
	s_nop 1
	v_permlane16_swap_b32_e32 v188, v190
	v_permlane16_swap_b32_e32 v189, v191
	global_store_dwordx4 v[194:195], v[188:191], off
	v_add_u32_e32 v79, 0xb0, v163
	v_add_u32_e32 v78, s4, v79
	v_and_b32_e32 v74, 0xfff, v78
	v_cndmask_b32_e64 v74, v115, v74, s[6:7]
	v_cvt_f32_u32_e32 v82, v74
	s_mov_b64 s[42:43], -1
	s_and_b64 vcc, exec, s[10:11]
	v_mul_f32_e32 v74, v159, v82
	v_floor_f32_e32 v74, v74
	v_fma_f32 v74, v159, v82, -v74
	v_sin_f32_e32 v76, v74
	v_cos_f32_e32 v80, v74
	v_mul_f32_e32 v74, v160, v82
	v_floor_f32_e32 v74, v74
	v_fma_f32 v74, v160, v82, -v74
	v_sin_f32_e32 v77, v74
	v_cos_f32_e32 v81, v74
	v_pk_mul_f32 v[74:75], v[66:67], v[76:77]
	v_pk_mul_f32 v[66:67], v[66:67], v[80:81]
	v_pk_fma_f32 v[74:75], v[70:71], v[80:81], v[74:75] neg_lo:[0,0,1] neg_hi:[0,0,1]
	v_pk_fma_f32 v[66:67], v[70:71], v[76:77], v[66:67]
	v_mul_f32_e32 v70, v161, v82
	v_floor_f32_e32 v70, v70
	v_fma_f32 v71, v161, v82, -v70
	v_sin_f32_e32 v70, v71
	v_cos_f32_e32 v80, v71
	v_mul_f32_e32 v71, v162, v82
	v_floor_f32_e32 v71, v71
	v_fma_f32 v76, v162, v82, -v71
	v_sin_f32_e32 v71, v76
	v_cos_f32_e32 v81, v76
	v_pk_mul_f32 v[76:77], v[68:69], v[70:71]
	v_pk_mul_f32 v[68:69], v[68:69], v[80:81]
	v_pk_fma_f32 v[76:77], v[72:73], v[80:81], v[76:77] neg_lo:[0,0,1] neg_hi:[0,0,1]
	v_pk_fma_f32 v[68:69], v[72:73], v[70:71], v[68:69]
	v_lshlrev_b32_e32 v80, 10, v79
	s_cbranch_vccnz .LBB0_188
	v_lshlrev_b32_e32 v70, 10, v79
	v_mov_b32_e32 v71, v1
	v_lshl_add_u64 v[72:73], v[70:71], 2, v[142:143]
	s_and_b64 vcc, exec, s[8:9]
	global_store_dwordx4 v[72:73], v[74:77], off
	global_store_dwordx4 v[72:73], v[66:69], off offset:128
	s_cbranch_vccnz .LBB0_187
	v_add_u32_e32 v70, 0xffff0000, v78
	v_lshrrev_b32_e32 v70, 6, v70
	v_mul_lo_u32 v70, v70, s57
	v_or_b32_e32 v70, v70, v114
	v_lshl_add_u32 v70, v70, 10, v170

; template <int EPI>
; __device__ __forceinline__ void gemm_epilogue(KP P, f32x4 (&acc)[2][2][4][2], int brow, int bcol, int wr, int wc, int fr_, int fq_, const float* sRu) {
;     ...
;         bfu* bdst;
;         float* fdst = nullptr;
;         if (isq) bdst = (bfu*)(P->ws + WS_Q) + (size_t)brow * 1024;
;         else if (prompt) { bdst = (bfu*)(P->ws + WS_KP) + (size_t)brow * 1024; fdst = P->out + O_KP + (size_t)brow * 1024; }
;         else { bdst = (bfu*)(P->ws + WS_KSM); fdst = P->out + O_KS + (size_t)(brow - MP) * 1024; }
;     ...
;               uint2 p1, p2;
;               p1.x = cvt_pk_bf16(o1[0], o1[1]); p1.y = cvt_pk_bf16(o1[2], o1[3]);
;               p2.x = cvt_pk_bf16(o2[0], o2[1]); p2.y = cvt_pk_bf16(o2[2], o2[3]);
;               *(uint2*)(bdst + bo) = p1;
;               *(uint2*)(bdst + bo + 32) = p2;
.LBB0_190:
	v_lshl_add_u64 v[66:67], v[0:1], 1, v[78:79]
	s_and_b64 vcc, exec, s[10:11]
	s_mov_b64 s[44:45], -1
	v_mov_b64_e32 v[184:185], v[70:71]
	v_mov_b64_e32 v[186:187], v[72:73]
	v_lshl_add_u64 v[192:193], v[66:67], 0, v[232:233]
	s_nop 1
	v_permlane16_swap_b32_e32 v184, v186
	v_permlane16_swap_b32_e32 v185, v187
	global_store_dwordx4 v[192:193], v[184:187], off
	s_cbranch_vccnz .LBB0_196
	s_and_b64 vcc, exec, s[8:9]
	s_mov_b64 s[40:41], -1
	s_cbranch_vccnz .LBB0_193
	s_load_dwordx2 s[40:41], s[0:1], 0xd8
	s_waitcnt lgkmcnt(0)
	s_add_u32 s25, s40, s36
	s_addc_u32 s27, s41, s37
	s_add_u32 s42, s25, 0x31ad8000
	s_addc_u32 s43, s27, 0
	s_mov_b64 s[40:41], 0

; template <int EPI>
; __device__ __forceinline__ void gemm_epilogue(KP P, f32x4 (&acc)[2][2][4][2], int brow, int bcol, int wr, int wc, int fr_, int fq_, const float* sRu) {
;     ...
;             __builtin_amdgcn_sched_barrier(0);
;             unsigned lr = lrow0b + ai * 128 + m * 16;
;             int row = brow + lr;
;             int pos = prompt ? (row & 4095) : 1024 + ((row - MP) & 63);
;             f32x4 x1 = acc[ai][bj][m][0], x2 = acc[ai][bj][m][1], o1, o2;
; #pragma unroll
;             for (int j = 0; j < 4; ++j) {
;               float rev = (float)pos * inv[j];
;               rev -= floorf(rev);
;               float sn = __builtin_amdgcn_sinf(rev), cs = __builtin_amdgcn_cosf(rev);
;               o1[j] = x1[j] * cs - x2[j] * sn;
;               o2[j] = x2[j] * cs + x1[j] * sn;
;             }
;             if (isq) {
;               uint2 p1, p2;
;               p1.x = cvt_pk_bf16(o1[0] * QSCALE, o1[1] * QSCALE); p1.y = cvt_pk_bf16(o1[2] * QSCALE, o1[3] * QSCALE);
;               p2.x = cvt_pk_bf16(o2[0] * QSCALE, o2[1] * QSCALE); p2.y = cvt_pk_bf16(o2[2] * QSCALE, o2[3] * QSCALE);
;               *(uint2*)(bdst + lr * 1024 + c1) = p1;
;               *(uint2*)(bdst + lr * 1024 + c1 + 32) = p2;
;             } else {
;               *(f32x4*)(fdst + lr * 1024 + c1) = o1;
;               *(f32x4*)(fdst + lr * 1024 + c1 + 32) = o2;
;               unsigned bo;
;               if (prompt) bo = lr * 1024 + c1;
;               else { int rs = row - MP; bo = ((rs >> 6) * SKV + 1024 + (rs & 63)) * 1024 + c1; }
;               uint2 p1, p2;
;               p1.x = cvt_pk_bf16(o1[0], o1[1]); p1.y = cvt_pk_bf16(o1[2], o1[3]);
;               p2.x = cvt_pk_bf16(o2[0], o2[1]); p2.y = cvt_pk_bf16(o2[2], o2[3]);
;               *(uint2*)(bdst + bo) = p1;
;               *(uint2*)(bdst + bo + 32) = p2;
.LBB0_204:
	v_add_u32_e32 v58, 16, v157
	v_mov_b32_e32 v75, v1
	v_and_b32_e32 v68, 63, v58
	v_lshl_add_u64 v[58:59], v[74:75], 1, v[76:77]
	v_mov_b64_e32 v[188:189], v[64:65]
	v_mov_b64_e32 v[190:191], v[72:73]
	v_lshl_add_u64 v[194:195], v[58:59], 0, v[232:233]
	s_nop 1
	v_permlane16_swap_b32_e32 v188, v190
	v_permlane16_swap_b32_e32 v189, v191
	global_store_dwordx4 v[194:195], v[188:191], off
	v_add_u32_e32 v66, 16, v82
	v_add_u32_e32 v65, s4, v66
	v_and_b32_e32 v58, 0xfff, v65
	v_or_b32_e32 v69, 0x400, v68
	v_cndmask_b32_e64 v58, v69, v58, s[6:7]
	v_cvt_f32_u32_e32 v64, v58
	s_mov_b64 s[34:35], -1
	s_and_b64 vcc, exec, s[10:11]
	v_mul_f32_e32 v58, v81, v64
	v_floor_f32_e32 v58, v58
	v_fma_f32 v58, v81, v64, -v58
	v_sin_f32_e32 v60, v58
	v_cos_f32_e32 v72, v58
	v_mul_f32_e32 v58, v78, v64
	v_floor_f32_e32 v58, v58
	v_fma_f32 v58, v78, v64, -v58
	v_sin_f32_e32 v61, v58
	v_cos_f32_e32 v73, v58
	v_pk_mul_f32 v[58:59], v[50:51], v[60:61]
	v_pk_mul_f32 v[50:51], v[50:51], v[72:73]
	v_pk_fma_f32 v[58:59], v[54:55], v[72:73], v[58:59] neg_lo:[0,0,1] neg_hi:[0,0,1]
	v_pk_fma_f32 v[50:51], v[54:55], v[60:61], v[50:51]
	v_mul_f32_e32 v54, v80, v64
	v_floor_f32_e32 v54, v54
	v_fma_f32 v55, v80, v64, -v54
	v_sin_f32_e32 v54, v55
	v_cos_f32_e32 v72, v55
	v_mul_f32_e32 v55, v79, v64
	v_floor_f32_e32 v55, v55
	v_fma_f32 v60, v79, v64, -v55
	v_sin_f32_e32 v55, v60
	v_cos_f32_e32 v73, v60
	v_pk_mul_f32 v[60:61], v[52:53], v[54:55]
	v_pk_mul_f32 v[52:53], v[52:53], v[72:73]
	v_pk_fma_f32 v[60:61], v[56:57], v[72:73], v[60:61] neg_lo:[0,0,1] neg_hi:[0,0,1]
	v_pk_fma_f32 v[52:53], v[56:57], v[54:55], v[52:53]
	v_lshlrev_b32_e32 v72, 10, v66
	s_cbranch_vccnz .LBB0_208
	v_lshlrev_b32_e32 v54, 10, v66
	v_mov_b32_e32 v55, v1
	v_lshl_add_u64 v[56:57], v[54:55], 2, v[70:71]
	s_and_b64 vcc, exec, s[8:9]
	global_store_dwordx4 v[56:57], v[58:61], off
	global_store_dwordx4 v[56:57], v[50:53], off offset:128
	s_cbranch_vccnz .LBB0_207
	v_add_u32_e32 v54, 0xffff0000, v65
	v_lshrrev_b32_e32 v54, 6, v54
	v_mul_lo_u32 v54, v54, s57
	v_or_b32_e32 v54, v54, v68
	v_lshl_add_u32 v54, v54, 10, v170

; template <int EPI>
; __device__ __forceinline__ void gemm_epilogue(KP P, f32x4 (&acc)[2][2][4][2], int brow, int bcol, int wr, int wc, int fr_, int fq_, const float* sRu) {
;     ...
;             __builtin_amdgcn_sched_barrier(0);
;             unsigned lr = lrow0b + ai * 128 + m * 16;
;             int row = brow + lr;
;             int pos = prompt ? (row & 4095) : 1024 + ((row - MP) & 63);
;             f32x4 x1 = acc[ai][bj][m][0], x2 = acc[ai][bj][m][1], o1, o2;
; #pragma unroll
;             for (int j = 0; j < 4; ++j) {
;               float rev = (float)pos * inv[j];
;               rev -= floorf(rev);
;               float sn = __builtin_amdgcn_sinf(rev), cs = __builtin_amdgcn_cosf(rev);
;               o1[j] = x1[j] * cs - x2[j] * sn;
;               o2[j] = x2[j] * cs + x1[j] * sn;
;             }
;             if (isq) {
;               uint2 p1, p2;
;               p1.x = cvt_pk_bf16(o1[0] * QSCALE, o1[1] * QSCALE); p1.y = cvt_pk_bf16(o1[2] * QSCALE, o1[3] * QSCALE);
;               p2.x = cvt_pk_bf16(o2[0] * QSCALE, o2[1] * QSCALE); p2.y = cvt_pk_bf16(o2[2] * QSCALE, o2[3] * QSCALE);
;               *(uint2*)(bdst + lr * 1024 + c1) = p1;
;               *(uint2*)(bdst + lr * 1024 + c1 + 32) = p2;
;             } else {
;               *(f32x4*)(fdst + lr * 1024 + c1) = o1;
;               *(f32x4*)(fdst + lr * 1024 + c1 + 32) = o2;
;               unsigned bo;
;               if (prompt) bo = lr * 1024 + c1;
;               else { int rs = row - MP; bo = ((rs >> 6) * SKV + 1024 + (rs & 63)) * 1024 + c1; }
;               uint2 p1, p2;
;               p1.x = cvt_pk_bf16(o1[0], o1[1]); p1.y = cvt_pk_bf16(o1[2], o1[3]);
;               p2.x = cvt_pk_bf16(o2[0], o2[1]); p2.y = cvt_pk_bf16(o2[2], o2[3]);
;               *(uint2*)(bdst + bo) = p1;
;               *(uint2*)(bdst + bo + 32) = p2;
.LBB0_210:
	v_mov_b32_e32 v65, v1
	v_xor_b32_e32 v58, 32, v83
	v_lshl_add_u64 v[50:51], v[64:65], 1, v[66:67]
	v_mov_b64_e32 v[184:185], v[54:55]
	v_mov_b64_e32 v[186:187], v[56:57]
	v_lshl_add_u64 v[192:193], v[50:51], 0, v[232:233]
	s_nop 1
	v_permlane16_swap_b32_e32 v184, v186
	v_permlane16_swap_b32_e32 v185, v187
	global_store_dwordx4 v[192:193], v[184:187], off
	v_add_u32_e32 v56, 32, v82
	v_add_u32_e32 v55, s4, v56
	s_movk_i32 s5, 0x400
	v_and_b32_e32 v50, 0xfff, v55
	v_bitop3_b32 v59, v83, s5, 32 bitop3:0xde
	v_cndmask_b32_e64 v50, v59, v50, s[6:7]
	v_cvt_f32_u32_e32 v54, v50
	s_mov_b64 s[34:35], -1
	s_and_b64 vcc, exec, s[10:11]
	v_mul_f32_e32 v50, v81, v54
	v_floor_f32_e32 v50, v50
	v_fma_f32 v50, v81, v54, -v50
	v_sin_f32_e32 v52, v50
	v_cos_f32_e32 v60, v50
	v_mul_f32_e32 v50, v78, v54
	v_floor_f32_e32 v50, v50
	v_fma_f32 v50, v78, v54, -v50
	v_sin_f32_e32 v53, v50
	v_cos_f32_e32 v61, v50
	v_pk_mul_f32 v[50:51], v[42:43], v[52:53]
	v_pk_mul_f32 v[42:43], v[42:43], v[60:61]
	v_pk_fma_f32 v[50:51], v[46:47], v[60:61], v[50:51] neg_lo:[0,0,1] neg_hi:[0,0,1]
	v_pk_fma_f32 v[42:43], v[46:47], v[52:53], v[42:43]
	v_mul_f32_e32 v46, v80, v54
	v_floor_f32_e32 v46, v46
	v_fma_f32 v47, v80, v54, -v46
	v_sin_f32_e32 v46, v47
	v_cos_f32_e32 v60, v47
	v_mul_f32_e32 v47, v79, v54
	v_floor_f32_e32 v47, v47
	v_fma_f32 v52, v79, v54, -v47
	v_sin_f32_e32 v47, v52
	v_cos_f32_e32 v61, v52
	v_pk_mul_f32 v[52:53], v[44:45], v[46:47]
	v_pk_mul_f32 v[44:45], v[44:45], v[60:61]
	v_pk_fma_f32 v[52:53], v[48:49], v[60:61], v[52:53] neg_lo:[0,0,1] neg_hi:[0,0,1]
	v_pk_fma_f32 v[44:45], v[48:49], v[46:47], v[44:45]
	v_lshlrev_b32_e32 v60, 10, v56
	s_cbranch_vccnz .LBB0_214
	v_lshlrev_b32_e32 v46, 10, v56
	v_mov_b32_e32 v47, v1
	v_lshl_add_u64 v[48:49], v[46:47], 2, v[70:71]
	s_and_b64 vcc, exec, s[8:9]
	global_store_dwordx4 v[48:49], v[50:53], off
	global_store_dwordx4 v[48:49], v[42:45], off offset:128
	s_cbranch_vccnz .LBB0_213
	v_add_u32_e32 v46, 0xffff0000, v55
	v_lshrrev_b32_e32 v46, 6, v46
	v_mul_lo_u32 v46, v46, s57
	v_or_b32_e32 v46, v46, v58
	v_lshl_add_u32 v46, v46, 10, v170

; template <int EPI>
; __device__ __forceinline__ void gemm_epilogue(KP P, f32x4 (&acc)[2][2][4][2], int brow, int bcol, int wr, int wc, int fr_, int fq_, const float* sRu) {
;     ...
;             __builtin_amdgcn_sched_barrier(0);
;             unsigned lr = lrow0b + ai * 128 + m * 16;
;             int row = brow + lr;
;             int pos = prompt ? (row & 4095) : 1024 + ((row - MP) & 63);
;             f32x4 x1 = acc[ai][bj][m][0], x2 = acc[ai][bj][m][1], o1, o2;
; #pragma unroll
;             for (int j = 0; j < 4; ++j) {
;               float rev = (float)pos * inv[j];
;               rev -= floorf(rev);
;               float sn = __builtin_amdgcn_sinf(rev), cs = __builtin_amdgcn_cosf(rev);
;               o1[j] = x1[j] * cs - x2[j] * sn;
;               o2[j] = x2[j] * cs + x1[j] * sn;
;             }
;             if (isq) {
;               uint2 p1, p2;
;               p1.x = cvt_pk_bf16(o1[0] * QSCALE, o1[1] * QSCALE); p1.y = cvt_pk_bf16(o1[2] * QSCALE, o1[3] * QSCALE);
;               p2.x = cvt_pk_bf16(o2[0] * QSCALE, o2[1] * QSCALE); p2.y = cvt_pk_bf16(o2[2] * QSCALE, o2[3] * QSCALE);
;               *(uint2*)(bdst + lr * 1024 + c1) = p1;
;               *(uint2*)(bdst + lr * 1024 + c1 + 32) = p2;
;             } else {
;               *(f32x4*)(fdst + lr * 1024 + c1) = o1;
;               *(f32x4*)(fdst + lr * 1024 + c1 + 32) = o2;
;               unsigned bo;
;               if (prompt) bo = lr * 1024 + c1;
;               else { int rs = row - MP; bo = ((rs >> 6) * SKV + 1024 + (rs & 63)) * 1024 + c1; }
;               uint2 p1, p2;
;               p1.x = cvt_pk_bf16(o1[0], o1[1]); p1.y = cvt_pk_bf16(o1[2], o1[3]);
;               p2.x = cvt_pk_bf16(o2[0], o2[1]); p2.y = cvt_pk_bf16(o2[2], o2[3]);
;               *(uint2*)(bdst + bo) = p1;
;               *(uint2*)(bdst + bo + 32) = p2;
.LBB0_216:
	v_add_u32_e32 v42, 48, v157
	v_mov_b32_e32 v55, v1
	v_and_b32_e32 v50, 63, v42
	v_lshl_add_u64 v[42:43], v[54:55], 1, v[56:57]
	v_mov_b64_e32 v[188:189], v[46:47]
	v_mov_b64_e32 v[190:191], v[48:49]
	v_lshl_add_u64 v[194:195], v[42:43], 0, v[232:233]
	s_nop 1
	v_permlane16_swap_b32_e32 v188, v190
	v_permlane16_swap_b32_e32 v189, v191
	global_store_dwordx4 v[194:195], v[188:191], off
	v_add_u32_e32 v48, 48, v82
	v_add_u32_e32 v47, s4, v48
	v_and_b32_e32 v42, 0xfff, v47
	v_or_b32_e32 v51, 0x400, v50
	v_cndmask_b32_e64 v42, v51, v42, s[6:7]
	v_cvt_f32_u32_e32 v46, v42
	s_mov_b64 s[34:35], -1
	s_and_b64 vcc, exec, s[10:11]
	v_mul_f32_e32 v42, v81, v46
	v_floor_f32_e32 v42, v42
	v_fma_f32 v42, v81, v46, -v42
	v_sin_f32_e32 v44, v42
	v_cos_f32_e32 v52, v42
	v_mul_f32_e32 v42, v78, v46
	v_floor_f32_e32 v42, v42
	v_fma_f32 v42, v78, v46, -v42
	v_sin_f32_e32 v45, v42
	v_cos_f32_e32 v53, v42
	v_pk_mul_f32 v[42:43], v[34:35], v[44:45]
	v_pk_mul_f32 v[34:35], v[34:35], v[52:53]
	v_pk_fma_f32 v[42:43], v[38:39], v[52:53], v[42:43] neg_lo:[0,0,1] neg_hi:[0,0,1]
	v_pk_fma_f32 v[34:35], v[38:39], v[44:45], v[34:35]
	v_mul_f32_e32 v38, v80, v46
	v_floor_f32_e32 v38, v38
	v_fma_f32 v39, v80, v46, -v38
	v_sin_f32_e32 v38, v39
	v_cos_f32_e32 v52, v39
	v_mul_f32_e32 v39, v79, v46
	v_floor_f32_e32 v39, v39
	v_fma_f32 v44, v79, v46, -v39
	v_sin_f32_e32 v39, v44
	v_cos_f32_e32 v53, v44
	v_pk_mul_f32 v[44:45], v[36:37], v[38:39]
	v_pk_mul_f32 v[36:37], v[36:37], v[52:53]
	v_pk_fma_f32 v[44:45], v[40:41], v[52:53], v[44:45] neg_lo:[0,0,1] neg_hi:[0,0,1]
	v_pk_fma_f32 v[36:37], v[40:41], v[38:39], v[36:37]
	v_lshlrev_b32_e32 v52, 10, v48
	s_cbranch_vccnz .LBB0_220
	v_lshlrev_b32_e32 v38, 10, v48
	v_mov_b32_e32 v39, v1
	v_lshl_add_u64 v[40:41], v[38:39], 2, v[70:71]
	s_and_b64 vcc, exec, s[8:9]
	global_store_dwordx4 v[40:41], v[42:45], off
	global_store_dwordx4 v[40:41], v[34:37], off offset:128
	s_cbranch_vccnz .LBB0_219
	v_add_u32_e32 v38, 0xffff0000, v47
	v_lshrrev_b32_e32 v38, 6, v38
	v_mul_lo_u32 v38, v38, s57
	v_or_b32_e32 v38, v38, v50
	v_lshl_add_u32 v38, v38, 10, v170

; template <int EPI>
; __device__ __forceinline__ void gemm_epilogue(KP P, f32x4 (&acc)[2][2][4][2], int brow, int bcol, int wr, int wc, int fr_, int fq_, const float* sRu) {
;     ...
;             __builtin_amdgcn_sched_barrier(0);
;             unsigned lr = lrow0b + ai * 128 + m * 16;
;             int row = brow + lr;
;             int pos = prompt ? (row & 4095) : 1024 + ((row - MP) & 63);
;             f32x4 x1 = acc[ai][bj][m][0], x2 = acc[ai][bj][m][1], o1, o2;
; #pragma unroll
;             for (int j = 0; j < 4; ++j) {
;               float rev = (float)pos * inv[j];
;               rev -= floorf(rev);
;               float sn = __builtin_amdgcn_sinf(rev), cs = __builtin_amdgcn_cosf(rev);
;               o1[j] = x1[j] * cs - x2[j] * sn;
;               o2[j] = x2[j] * cs + x1[j] * sn;
;             }
;             if (isq) {
;               uint2 p1, p2;
;               p1.x = cvt_pk_bf16(o1[0] * QSCALE, o1[1] * QSCALE); p1.y = cvt_pk_bf16(o1[2] * QSCALE, o1[3] * QSCALE);
;               p2.x = cvt_pk_bf16(o2[0] * QSCALE, o2[1] * QSCALE); p2.y = cvt_pk_bf16(o2[2] * QSCALE, o2[3] * QSCALE);
;               *(uint2*)(bdst + lr * 1024 + c1) = p1;
;               *(uint2*)(bdst + lr * 1024 + c1 + 32) = p2;
;             } else {
;               *(f32x4*)(fdst + lr * 1024 + c1) = o1;
;               *(f32x4*)(fdst + lr * 1024 + c1 + 32) = o2;
;               unsigned bo;
;               if (prompt) bo = lr * 1024 + c1;
;               else { int rs = row - MP; bo = ((rs >> 6) * SKV + 1024 + (rs & 63)) * 1024 + c1; }
;               uint2 p1, p2;
;               p1.x = cvt_pk_bf16(o1[0], o1[1]); p1.y = cvt_pk_bf16(o1[2], o1[3]);
;               p2.x = cvt_pk_bf16(o2[0], o2[1]); p2.y = cvt_pk_bf16(o2[2], o2[3]);
;               *(uint2*)(bdst + bo) = p1;
;               *(uint2*)(bdst + bo + 32) = p2;
.LBB0_222:
	v_mov_b32_e32 v47, v1
	v_lshl_add_u64 v[34:35], v[46:47], 1, v[48:49]
	v_mov_b64_e32 v[184:185], v[38:39]
	v_mov_b64_e32 v[186:187], v[40:41]
	v_lshl_add_u64 v[192:193], v[34:35], 0, v[232:233]
	s_nop 1
	v_permlane16_swap_b32_e32 v184, v186
	v_permlane16_swap_b32_e32 v185, v187
	global_store_dwordx4 v[192:193], v[184:187], off
	v_add_u32_e32 v40, 0x80, v82
	v_add_u32_e32 v39, s4, v40
	v_and_b32_e32 v34, 0xfff, v39
	v_cndmask_b32_e64 v34, v84, v34, s[6:7]
	v_cvt_f32_u32_e32 v38, v34
	s_mov_b64 s[34:35], -1
	s_and_b64 vcc, exec, s[10:11]
	v_mul_f32_e32 v34, v81, v38
	v_floor_f32_e32 v34, v34
	v_fma_f32 v34, v81, v38, -v34
	v_sin_f32_e32 v36, v34
	v_cos_f32_e32 v42, v34
	v_mul_f32_e32 v34, v78, v38
	v_floor_f32_e32 v34, v34
	v_fma_f32 v34, v78, v38, -v34
	v_sin_f32_e32 v37, v34
	v_cos_f32_e32 v43, v34
	v_pk_mul_f32 v[34:35], v[26:27], v[36:37]
	v_pk_mul_f32 v[26:27], v[26:27], v[42:43]
	v_pk_fma_f32 v[34:35], v[30:31], v[42:43], v[34:35] neg_lo:[0,0,1] neg_hi:[0,0,1]
	v_pk_fma_f32 v[26:27], v[30:31], v[36:37], v[26:27]
	v_mul_f32_e32 v30, v80, v38
	v_floor_f32_e32 v30, v30
	v_fma_f32 v31, v80, v38, -v30
	v_sin_f32_e32 v30, v31
	v_cos_f32_e32 v42, v31
	v_mul_f32_e32 v31, v79, v38
	v_floor_f32_e32 v31, v31
	v_fma_f32 v36, v79, v38, -v31
	v_sin_f32_e32 v31, v36
	v_cos_f32_e32 v43, v36
	v_pk_mul_f32 v[36:37], v[28:29], v[30:31]
	v_pk_mul_f32 v[28:29], v[28:29], v[42:43]
	v_pk_fma_f32 v[36:37], v[32:33], v[42:43], v[36:37] neg_lo:[0,0,1] neg_hi:[0,0,1]
	v_pk_fma_f32 v[28:29], v[32:33], v[30:31], v[28:29]
	v_lshlrev_b32_e32 v42, 10, v40
	s_cbranch_vccnz .LBB0_226
	v_lshlrev_b32_e32 v30, 10, v40
	v_mov_b32_e32 v31, v1
	v_lshl_add_u64 v[32:33], v[30:31], 2, v[70:71]
	s_and_b64 vcc, exec, s[8:9]
	global_store_dwordx4 v[32:33], v[34:37], off
	global_store_dwordx4 v[32:33], v[26:29], off offset:128
	s_cbranch_vccnz .LBB0_225
	v_add_u32_e32 v30, 0xffff0000, v39
	v_lshrrev_b32_e32 v30, 6, v30
	v_mul_lo_u32 v30, v30, s57
	v_or_b32_e32 v30, v30, v83
	v_lshl_add_u32 v30, v30, 10, v170

; template <int EPI>
; __device__ __forceinline__ void gemm_epilogue(KP P, f32x4 (&acc)[2][2][4][2], int brow, int bcol, int wr, int wc, int fr_, int fq_, const float* sRu) {
;     ...
;             __builtin_amdgcn_sched_barrier(0);
;             unsigned lr = lrow0b + ai * 128 + m * 16;
;             int row = brow + lr;
;             int pos = prompt ? (row & 4095) : 1024 + ((row - MP) & 63);
;             f32x4 x1 = acc[ai][bj][m][0], x2 = acc[ai][bj][m][1], o1, o2;
; #pragma unroll
;             for (int j = 0; j < 4; ++j) {
;               float rev = (float)pos * inv[j];
;               rev -= floorf(rev);
;               float sn = __builtin_amdgcn_sinf(rev), cs = __builtin_amdgcn_cosf(rev);
;               o1[j] = x1[j] * cs - x2[j] * sn;
;               o2[j] = x2[j] * cs + x1[j] * sn;
;             }
;             if (isq) {
;               uint2 p1, p2;
;               p1.x = cvt_pk_bf16(o1[0] * QSCALE, o1[1] * QSCALE); p1.y = cvt_pk_bf16(o1[2] * QSCALE, o1[3] * QSCALE);
;               p2.x = cvt_pk_bf16(o2[0] * QSCALE, o2[1] * QSCALE); p2.y = cvt_pk_bf16(o2[2] * QSCALE, o2[3] * QSCALE);
;               *(uint2*)(bdst + lr * 1024 + c1) = p1;
;               *(uint2*)(bdst + lr * 1024 + c1 + 32) = p2;
;             } else {
;               *(f32x4*)(fdst + lr * 1024 + c1) = o1;
;               *(f32x4*)(fdst + lr * 1024 + c1 + 32) = o2;
;               unsigned bo;
;               if (prompt) bo = lr * 1024 + c1;
;               else { int rs = row - MP; bo = ((rs >> 6) * SKV + 1024 + (rs & 63)) * 1024 + c1; }
;               uint2 p1, p2;
;               p1.x = cvt_pk_bf16(o1[0], o1[1]); p1.y = cvt_pk_bf16(o1[2], o1[3]);
;               p2.x = cvt_pk_bf16(o2[0], o2[1]); p2.y = cvt_pk_bf16(o2[2], o2[3]);
;               *(uint2*)(bdst + bo) = p1;
;               *(uint2*)(bdst + bo + 32) = p2;
.LBB0_228:
	v_mov_b32_e32 v39, v1
	v_lshl_add_u64 v[26:27], v[38:39], 1, v[40:41]
	v_mov_b64_e32 v[188:189], v[30:31]
	v_mov_b64_e32 v[190:191], v[32:33]
	v_lshl_add_u64 v[194:195], v[26:27], 0, v[232:233]
	s_nop 1
	v_permlane16_swap_b32_e32 v188, v190
	v_permlane16_swap_b32_e32 v189, v191
	global_store_dwordx4 v[194:195], v[188:191], off
	v_add_u32_e32 v32, 0x90, v82
	v_add_u32_e32 v31, s4, v32
	v_and_b32_e32 v26, 0xfff, v31
	v_cndmask_b32_e64 v26, v69, v26, s[6:7]
	v_cvt_f32_u32_e32 v30, v26
	s_mov_b64 s[34:35], -1
	s_and_b64 vcc, exec, s[10:11]
	v_mul_f32_e32 v26, v81, v30
	v_floor_f32_e32 v26, v26
	v_fma_f32 v26, v81, v30, -v26
	v_sin_f32_e32 v28, v26
	v_cos_f32_e32 v34, v26
	v_mul_f32_e32 v26, v78, v30
	v_floor_f32_e32 v26, v26
	v_fma_f32 v26, v78, v30, -v26
	v_sin_f32_e32 v29, v26
	v_cos_f32_e32 v35, v26
	v_pk_mul_f32 v[26:27], v[18:19], v[28:29]
	v_pk_mul_f32 v[18:19], v[18:19], v[34:35]
	v_pk_fma_f32 v[26:27], v[22:23], v[34:35], v[26:27] neg_lo:[0,0,1] neg_hi:[0,0,1]
	v_pk_fma_f32 v[18:19], v[22:23], v[28:29], v[18:19]
	v_mul_f32_e32 v22, v80, v30
	v_floor_f32_e32 v22, v22
	v_fma_f32 v23, v80, v30, -v22
	v_sin_f32_e32 v22, v23
	v_cos_f32_e32 v34, v23
	v_mul_f32_e32 v23, v79, v30
	v_floor_f32_e32 v23, v23
	v_fma_f32 v28, v79, v30, -v23
	v_sin_f32_e32 v23, v28
	v_cos_f32_e32 v35, v28
	v_pk_mul_f32 v[28:29], v[20:21], v[22:23]
	v_pk_mul_f32 v[20:21], v[20:21], v[34:35]
	v_pk_fma_f32 v[28:29], v[24:25], v[34:35], v[28:29] neg_lo:[0,0,1] neg_hi:[0,0,1]
	v_pk_fma_f32 v[20:21], v[24:25], v[22:23], v[20:21]
	v_lshlrev_b32_e32 v34, 10, v32
	s_cbranch_vccnz .LBB0_232
	v_lshlrev_b32_e32 v22, 10, v32
	v_mov_b32_e32 v23, v1
	v_lshl_add_u64 v[24:25], v[22:23], 2, v[70:71]
	s_and_b64 vcc, exec, s[8:9]
	global_store_dwordx4 v[24:25], v[26:29], off
	global_store_dwordx4 v[24:25], v[18:21], off offset:128
	s_cbranch_vccnz .LBB0_231
	v_add_u32_e32 v22, 0xffff0000, v31
	v_lshrrev_b32_e32 v22, 6, v22
	v_mul_lo_u32 v22, v22, s57
	v_or_b32_e32 v22, v22, v68
	v_lshl_add_u32 v22, v22, 10, v170

; template <int EPI>
; __device__ __forceinline__ void gemm_epilogue(KP P, f32x4 (&acc)[2][2][4][2], int brow, int bcol, int wr, int wc, int fr_, int fq_, const float* sRu) {
;     ...
;             __builtin_amdgcn_sched_barrier(0);
;             unsigned lr = lrow0b + ai * 128 + m * 16;
;             int row = brow + lr;
;             int pos = prompt ? (row & 4095) : 1024 + ((row - MP) & 63);
;             f32x4 x1 = acc[ai][bj][m][0], x2 = acc[ai][bj][m][1], o1, o2;
; #pragma unroll
;             for (int j = 0; j < 4; ++j) {
;               float rev = (float)pos * inv[j];
;               rev -= floorf(rev);
;               float sn = __builtin_amdgcn_sinf(rev), cs = __builtin_amdgcn_cosf(rev);
;               o1[j] = x1[j] * cs - x2[j] * sn;
;               o2[j] = x2[j] * cs + x1[j] * sn;
;             }
;             if (isq) {
;               uint2 p1, p2;
;               p1.x = cvt_pk_bf16(o1[0] * QSCALE, o1[1] * QSCALE); p1.y = cvt_pk_bf16(o1[2] * QSCALE, o1[3] * QSCALE);
;               p2.x = cvt_pk_bf16(o2[0] * QSCALE, o2[1] * QSCALE); p2.y = cvt_pk_bf16(o2[2] * QSCALE, o2[3] * QSCALE);
;               *(uint2*)(bdst + lr * 1024 + c1) = p1;
;               *(uint2*)(bdst + lr * 1024 + c1 + 32) = p2;
;             } else {
;               *(f32x4*)(fdst + lr * 1024 + c1) = o1;
;               *(f32x4*)(fdst + lr * 1024 + c1 + 32) = o2;
;               unsigned bo;
;               if (prompt) bo = lr * 1024 + c1;
;               else { int rs = row - MP; bo = ((rs >> 6) * SKV + 1024 + (rs & 63)) * 1024 + c1; }
;               uint2 p1, p2;
;               p1.x = cvt_pk_bf16(o1[0], o1[1]); p1.y = cvt_pk_bf16(o1[2], o1[3]);
;               p2.x = cvt_pk_bf16(o2[0], o2[1]); p2.y = cvt_pk_bf16(o2[2], o2[3]);
;               *(uint2*)(bdst + bo) = p1;
;               *(uint2*)(bdst + bo + 32) = p2;
.LBB0_234:
	v_mov_b32_e32 v31, v1
	v_lshl_add_u64 v[18:19], v[30:31], 1, v[32:33]
	v_mov_b64_e32 v[184:185], v[22:23]
	v_mov_b64_e32 v[186:187], v[24:25]
	v_lshl_add_u64 v[192:193], v[18:19], 0, v[232:233]
	s_nop 1
	v_permlane16_swap_b32_e32 v184, v186
	v_permlane16_swap_b32_e32 v185, v187
	global_store_dwordx4 v[192:193], v[184:187], off
	v_add_u32_e32 v24, 0xa0, v82
	v_add_u32_e32 v23, s4, v24
	v_and_b32_e32 v18, 0xfff, v23
	v_cndmask_b32_e64 v18, v59, v18, s[6:7]
	v_cvt_f32_u32_e32 v22, v18
	s_mov_b64 s[34:35], -1
	s_and_b64 vcc, exec, s[10:11]
	v_mul_f32_e32 v18, v81, v22
	v_floor_f32_e32 v18, v18
	v_fma_f32 v18, v81, v22, -v18
	v_sin_f32_e32 v20, v18
	v_cos_f32_e32 v26, v18
	v_mul_f32_e32 v18, v78, v22
	v_floor_f32_e32 v18, v18
	v_fma_f32 v18, v78, v22, -v18
	v_sin_f32_e32 v21, v18
	v_cos_f32_e32 v27, v18
	v_pk_mul_f32 v[18:19], v[10:11], v[20:21]
	v_pk_mul_f32 v[10:11], v[10:11], v[26:27]
	v_pk_fma_f32 v[18:19], v[14:15], v[26:27], v[18:19] neg_lo:[0,0,1] neg_hi:[0,0,1]
	v_pk_fma_f32 v[10:11], v[14:15], v[20:21], v[10:11]
	v_mul_f32_e32 v14, v80, v22
	v_floor_f32_e32 v14, v14
	v_fma_f32 v15, v80, v22, -v14
	v_sin_f32_e32 v14, v15
	v_cos_f32_e32 v26, v15
	v_mul_f32_e32 v15, v79, v22
	v_floor_f32_e32 v15, v15
	v_fma_f32 v20, v79, v22, -v15
	v_sin_f32_e32 v15, v20
	v_cos_f32_e32 v27, v20
	v_pk_mul_f32 v[20:21], v[12:13], v[14:15]
	v_pk_mul_f32 v[12:13], v[12:13], v[26:27]
	v_pk_fma_f32 v[20:21], v[16:17], v[26:27], v[20:21] neg_lo:[0,0,1] neg_hi:[0,0,1]
	v_pk_fma_f32 v[12:13], v[16:17], v[14:15], v[12:13]
	v_lshlrev_b32_e32 v26, 10, v24
	s_cbranch_vccnz .LBB0_238
	v_lshlrev_b32_e32 v14, 10, v24
	v_mov_b32_e32 v15, v1
	v_lshl_add_u64 v[16:17], v[14:15], 2, v[70:71]
	s_and_b64 vcc, exec, s[8:9]
	global_store_dwordx4 v[16:17], v[18:21], off
	global_store_dwordx4 v[16:17], v[10:13], off offset:128
	s_cbranch_vccnz .LBB0_237
	v_add_u32_e32 v14, 0xffff0000, v23
	v_lshrrev_b32_e32 v14, 6, v14
	v_mul_lo_u32 v14, v14, s57
	v_or_b32_e32 v14, v14, v58
	v_lshl_add_u32 v14, v14, 10, v170

; template <int EPI>
; __device__ __forceinline__ void gemm_epilogue(KP P, f32x4 (&acc)[2][2][4][2], int brow, int bcol, int wr, int wc, int fr_, int fq_, const float* sRu) {
;     ...
;             __builtin_amdgcn_sched_barrier(0);
;             unsigned lr = lrow0b + ai * 128 + m * 16;
;             int row = brow + lr;
;             int pos = prompt ? (row & 4095) : 1024 + ((row - MP) & 63);
;             f32x4 x1 = acc[ai][bj][m][0], x2 = acc[ai][bj][m][1], o1, o2;
; #pragma unroll
;             for (int j = 0; j < 4; ++j) {
;               float rev = (float)pos * inv[j];
;               rev -= floorf(rev);
;               float sn = __builtin_amdgcn_sinf(rev), cs = __builtin_amdgcn_cosf(rev);
;               o1[j] = x1[j] * cs - x2[j] * sn;
;               o2[j] = x2[j] * cs + x1[j] * sn;
;             }
;             if (isq) {
;               uint2 p1, p2;
;               p1.x = cvt_pk_bf16(o1[0] * QSCALE, o1[1] * QSCALE); p1.y = cvt_pk_bf16(o1[2] * QSCALE, o1[3] * QSCALE);
;               p2.x = cvt_pk_bf16(o2[0] * QSCALE, o2[1] * QSCALE); p2.y = cvt_pk_bf16(o2[2] * QSCALE, o2[3] * QSCALE);
;               *(uint2*)(bdst + lr * 1024 + c1) = p1;
;               *(uint2*)(bdst + lr * 1024 + c1 + 32) = p2;
;             } else {
;               *(f32x4*)(fdst + lr * 1024 + c1) = o1;
;               *(f32x4*)(fdst + lr * 1024 + c1 + 32) = o2;
;               unsigned bo;
;               if (prompt) bo = lr * 1024 + c1;
;               else { int rs = row - MP; bo = ((rs >> 6) * SKV + 1024 + (rs & 63)) * 1024 + c1; }
;               uint2 p1, p2;
;               p1.x = cvt_pk_bf16(o1[0], o1[1]); p1.y = cvt_pk_bf16(o1[2], o1[3]);
;               p2.x = cvt_pk_bf16(o2[0], o2[1]); p2.y = cvt_pk_bf16(o2[2], o2[3]);
;               *(uint2*)(bdst + bo) = p1;
;               *(uint2*)(bdst + bo + 32) = p2;
.LBB0_240:
	v_mov_b32_e32 v23, v1
	v_lshl_add_u64 v[10:11], v[22:23], 1, v[24:25]
	v_mov_b64_e32 v[188:189], v[14:15]
	v_mov_b64_e32 v[190:191], v[16:17]
	v_lshl_add_u64 v[194:195], v[10:11], 0, v[232:233]
	s_nop 1
	v_permlane16_swap_b32_e32 v188, v190
	v_permlane16_swap_b32_e32 v189, v191
	global_store_dwordx4 v[194:195], v[188:191], off
	v_add_u32_e32 v15, 0xb0, v82
	v_add_u32_e32 v14, s4, v15
	v_and_b32_e32 v10, 0xfff, v14
	v_cndmask_b32_e64 v10, v51, v10, s[6:7]
	v_cvt_f32_u32_e32 v18, v10
	s_mov_b64 s[4:5], -1
	s_and_b64 vcc, exec, s[10:11]
	v_mul_f32_e32 v10, v81, v18
	v_floor_f32_e32 v10, v10
	v_fma_f32 v10, v81, v18, -v10
	v_sin_f32_e32 v12, v10
	v_cos_f32_e32 v16, v10
	v_mul_f32_e32 v10, v78, v18
	v_floor_f32_e32 v10, v10
	v_fma_f32 v10, v78, v18, -v10
	v_sin_f32_e32 v13, v10
	v_cos_f32_e32 v17, v10
	v_pk_mul_f32 v[10:11], v[2:3], v[12:13]
	v_pk_mul_f32 v[2:3], v[2:3], v[16:17]
	v_pk_fma_f32 v[10:11], v[6:7], v[16:17], v[10:11] neg_lo:[0,0,1] neg_hi:[0,0,1]
	v_pk_fma_f32 v[2:3], v[6:7], v[12:13], v[2:3]
	v_mul_f32_e32 v6, v80, v18
	v_floor_f32_e32 v6, v6
	v_fma_f32 v7, v80, v18, -v6
	v_sin_f32_e32 v6, v7
	v_cos_f32_e32 v16, v7
	v_mul_f32_e32 v7, v79, v18
	v_floor_f32_e32 v7, v7
	v_fma_f32 v12, v79, v18, -v7
	v_sin_f32_e32 v7, v12
	v_cos_f32_e32 v17, v12
	v_pk_mul_f32 v[12:13], v[4:5], v[6:7]
	v_pk_mul_f32 v[4:5], v[4:5], v[16:17]
	v_pk_fma_f32 v[12:13], v[8:9], v[16:17], v[12:13] neg_lo:[0,0,1] neg_hi:[0,0,1]
	v_pk_fma_f32 v[4:5], v[8:9], v[6:7], v[4:5]
	v_lshlrev_b32_e32 v16, 10, v15
	s_cbranch_vccnz .LBB0_244
	v_lshlrev_b32_e32 v6, 10, v15
	v_mov_b32_e32 v7, v1
	v_lshl_add_u64 v[8:9], v[6:7], 2, v[70:71]
	s_and_b64 vcc, exec, s[8:9]
	global_store_dwordx4 v[8:9], v[10:13], off
	global_store_dwordx4 v[8:9], v[2:5], off offset:128
	s_cbranch_vccnz .LBB0_243
	v_add_u32_e32 v6, 0xffff0000, v14
	v_lshrrev_b32_e32 v6, 6, v6
	v_mul_lo_u32 v6, v6, s57
	v_or_b32_e32 v6, v6, v50
	v_lshl_add_u32 v6, v6, 10, v170

; #define PG8_STAGE(bufoff, gbase) do { _Pragma("unroll") for (int _i = 0; _i < 2; ++_i) \
;     __builtin_amdgcn_global_load_lds((const unsigned*)((const char*)(gbase) + voff[_i]), (LAS unsigned*)(lds + (bufoff) + ldsw + _i * 8192), 16, 0, 0); } while (0)
; #define PG8_LDA(dst, b, h) do { _Pragma("unroll") for (int m = 0; m < 4; ++m) _Pragma("unroll") for (int k = 0; k < 2; ++k) dst[m][k] = *(const LAS bf16x8*)(lds + PG8_SA(b, h) + aoff + m * 2048 + k * 1024); } while (0)
; #define PG8_LDB(dst, b, h) do { _Pragma("unroll") for (int n = 0; n < 2; ++n) _Pragma("unroll") for (int k = 0; k < 2; ++k) dst[n][k] = *(const LAS bf16x8*)(lds + PG8_SB(b, h) + boff + n * 2048 + k * 1024); } while (0)
; #define PG8_MMA(ai, bj, At, Bt_) do { __builtin_amdgcn_s_setprio(1); _Pragma("unroll") for (int m = 0; m < 4; ++m) _Pragma("unroll") for (int n = 0; n < 2; ++n) _Pragma("unroll") for (int k = 0; k < 2; ++k) \
;     acc[ai][bj][m][n] = __builtin_amdgcn_mfma_f32_16x16x32_bf16(Bt_[n][k], At[m][k], acc[ai][bj][m][n], 0, 0, 0); __builtin_amdgcn_s_setprio(0); } while (0)
; #define PG8_WAIT_V(n) asm volatile("s_waitcnt vmcnt(" #n ")" ::: "memory")
; #define PG8_WAIT_L(n) asm volatile("s_waitcnt lgkmcnt(" #n ")" ::: "memory")
; #define PG8_BAR __builtin_amdgcn_s_barrier()
; #define PG8_SCHED __builtin_amdgcn_sched_barrier(0)
; template <int EPI>
; __device__ __forceinline__ void gemm_phase(KP P, const bfu* __restrict__ A, const bfu* __restrict__ Bt, int K, int ntn, char* smem, const int wv) {
;     ...
;       PG8_LDB(B0, 0, 0); PG8_SCHED; PG8_LDA(At, 0, 0); PG8_STAGE(PG8_SA(1, 1), a1 + hstep);
;       PG8_WAIT_L(8); PG8_BAR; PG8_WAIT_L(0); PG8_MMA(0, 0, At, B0); PG8_BAR; PG8_SCHED;
;       PG8_LDB(B1, 0, 1); PG8_STAGE(PG8_SB(0, 0), b2);
;       PG8_BAR; PG8_WAIT_L(0); PG8_MMA(0, 1, At, B1); PG8_BAR;
;       PG8_LDA(At, 0, 1); PG8_STAGE(PG8_SA(0, 0), a2);
;       PG8_BAR; PG8_WAIT_L(0); PG8_MMA(1, 0, At, B0); PG8_BAR; PG8_SCHED;
;       PG8_STAGE(PG8_SB(0, 1), b2 + hstep);
;       PG8_WAIT_V(6); PG8_BAR; PG8_MMA(1, 1, At, B1); PG8_BAR;
.LBB0_264:
	v_add_u32_e32 v0, s35, v144
	s_add_u32 s24, s75, s22
	ds_read_b128 v[150:153], v0
	ds_read_b128 v[154:157], v0 offset:1024
	ds_read_b128 v[158:161], v0 offset:2048
	ds_read_b128 v[180:183], v0 offset:3072
	s_addc_u32 s25, s76, s23
	s_add_u32 s24, s24, 0x3780100
	s_addc_u32 s25, s25, 0
	s_add_u32 s80, s77, s22
	s_addc_u32 s81, s78, s23
	s_cmpk_eq_i32 s22, 0x700
	s_cselect_b32 s27, s71, s25
	s_cselect_b32 s26, s15, s24
	s_cselect_b32 s25, s74, s81
	s_cselect_b32 s24, s11, s80
	v_lshl_add_u64 v[162:163], v[138:139], 0, s[22:23]
	s_add_i32 m0, s38, 0xc000
	ds_read_b128 v[184:187], v145
	ds_read_b128 v[188:191], v145 offset:1024
	ds_read_b128 v[192:195], v145 offset:2048
	ds_read_b128 v[196:199], v145 offset:3072
	ds_read_b128 v[200:203], v145 offset:4096
	ds_read_b128 v[204:207], v145 offset:5120
	ds_read_b128 v[208:211], v145 offset:6144
	ds_read_b128 v[212:215], v145 offset:7168
	global_load_lds_dwordx4 v[162:163], off
	v_lshl_add_u64 v[162:163], v[140:141], 0, s[22:23]
	s_add_i32 m0, s38, 0xe000
	s_nop 0
	global_load_lds_dwordx4 v[162:163], off
	s_waitcnt lgkmcnt(8)
	s_barrier
	s_waitcnt lgkmcnt(0)
	s_setprio 1
	s_waitcnt lgkmcnt(0)
	v_mfma_f32_16x16x32_bf16 v[126:129], v[150:153], v[184:187], v[126:129]
	v_mfma_f32_16x16x32_bf16 v[122:125], v[158:161], v[184:187], v[122:125]
	v_mfma_f32_16x16x32_bf16 v[110:113], v[150:153], v[192:195], v[110:113]
	v_mfma_f32_16x16x32_bf16 v[106:109], v[158:161], v[192:195], v[106:109]
	v_mfma_f32_16x16x32_bf16 v[94:97], v[150:153], v[200:203], v[94:97]
	v_mfma_f32_16x16x32_bf16 v[90:93], v[158:161], v[200:203], v[90:93]
	v_mfma_f32_16x16x32_bf16 v[78:81], v[150:153], v[208:211], v[78:81]
	v_mfma_f32_16x16x32_bf16 v[74:77], v[158:161], v[208:211], v[74:77]
	v_mfma_f32_16x16x32_bf16 v[126:129], v[154:157], v[188:191], v[126:129]
	v_mfma_f32_16x16x32_bf16 v[122:125], v[180:183], v[188:191], v[122:125]
	v_mfma_f32_16x16x32_bf16 v[110:113], v[154:157], v[196:199], v[110:113]
	v_mfma_f32_16x16x32_bf16 v[106:109], v[180:183], v[196:199], v[106:109]
	v_mfma_f32_16x16x32_bf16 v[94:97], v[154:157], v[204:207], v[94:97]
	v_mfma_f32_16x16x32_bf16 v[90:93], v[180:183], v[204:207], v[90:93]
	v_mfma_f32_16x16x32_bf16 v[78:81], v[154:157], v[212:215], v[78:81]
	v_mfma_f32_16x16x32_bf16 v[74:77], v[180:183], v[212:215], v[74:77]
	s_setprio 0
	s_barrier
	s_mov_b32 m0, s36
	v_add_u32_e32 v0, s40, v144
	v_lshl_add_u64 v[162:163], s[24:25], 0, v[130:131]
	ds_read_b128 v[216:219], v0
	ds_read_b128 v[220:223], v0 offset:1024
	ds_read_b128 v[224:227], v0 offset:2048
	ds_read_b128 v[228:231], v0 offset:3072
	global_load_lds_dwordx4 v[162:163], off
	v_lshl_add_u64 v[232:233], s[24:25], 0, v[132:133]
	s_mov_b32 m0, s37
	s_nop 0
	global_load_lds_dwordx4 v[232:233], off
	s_barrier
	s_waitcnt lgkmcnt(0)
	s_setprio 1
	s_waitcnt lgkmcnt(0)
	v_mfma_f32_16x16x32_bf16 v[118:121], v[216:219], v[184:187], v[118:121]
	v_mfma_f32_16x16x32_bf16 v[114:117], v[224:227], v[184:187], v[114:117]
	v_mfma_f32_16x16x32_bf16 v[102:105], v[216:219], v[192:195], v[102:105]
	v_mfma_f32_16x16x32_bf16 v[98:101], v[224:227], v[192:195], v[98:101]
	v_mfma_f32_16x16x32_bf16 v[86:89], v[216:219], v[200:203], v[86:89]
	v_mfma_f32_16x16x32_bf16 v[82:85], v[224:227], v[200:203], v[82:85]
	v_mfma_f32_16x16x32_bf16 v[70:73], v[216:219], v[208:211], v[70:73]
	v_mfma_f32_16x16x32_bf16 v[66:69], v[224:227], v[208:211], v[66:69]
	v_mfma_f32_16x16x32_bf16 v[118:121], v[220:223], v[188:191], v[118:121]
	v_mfma_f32_16x16x32_bf16 v[114:117], v[228:231], v[188:191], v[114:117]
	v_mfma_f32_16x16x32_bf16 v[102:105], v[220:223], v[196:199], v[102:105]
	v_mfma_f32_16x16x32_bf16 v[98:101], v[228:231], v[196:199], v[98:101]
	v_mfma_f32_16x16x32_bf16 v[86:89], v[220:223], v[204:207], v[86:89]
	v_mfma_f32_16x16x32_bf16 v[82:85], v[228:231], v[204:207], v[82:85]
	v_mfma_f32_16x16x32_bf16 v[70:73], v[220:223], v[212:215], v[70:73]
	v_mfma_f32_16x16x32_bf16 v[66:69], v[228:231], v[212:215], v[66:69]
	s_setprio 0
	s_mov_b32 m0, s38
	v_lshl_add_u64 v[234:235], s[26:27], 0, v[130:131]
	s_barrier
	ds_read_b128 v[184:187], v145 offset:16384
	ds_read_b128 v[188:191], v145 offset:17408
	ds_read_b128 v[192:195], v145 offset:18432
	ds_read_b128 v[196:199], v145 offset:19456
	ds_read_b128 v[200:203], v145 offset:20480
	ds_read_b128 v[204:207], v145 offset:21504
	ds_read_b128 v[208:211], v145 offset:22528
	ds_read_b128 v[212:215], v145 offset:23552
	global_load_lds_dwordx4 v[234:235], off
	v_lshl_add_u64 v[236:237], s[26:27], 0, v[132:133]
	s_mov_b32 m0, s39
	s_nop 0
	global_load_lds_dwordx4 v[236:237], off
	s_barrier
	s_waitcnt lgkmcnt(0)
	s_setprio 1
	s_waitcnt lgkmcnt(0)
	v_mfma_f32_16x16x32_bf16 v[62:65], v[150:153], v[184:187], v[62:65]
	v_mfma_f32_16x16x32_bf16 v[58:61], v[158:161], v[184:187], v[58:61]
	v_mfma_f32_16x16x32_bf16 v[46:49], v[150:153], v[192:195], v[46:49]
	v_mfma_f32_16x16x32_bf16 v[42:45], v[158:161], v[192:195], v[42:45]
	v_mfma_f32_16x16x32_bf16 v[30:33], v[150:153], v[200:203], v[30:33]
	v_mfma_f32_16x16x32_bf16 v[26:29], v[158:161], v[200:203], v[26:29]
	v_mfma_f32_16x16x32_bf16 v[14:17], v[150:153], v[208:211], v[14:17]
	v_mfma_f32_16x16x32_bf16 v[10:13], v[158:161], v[208:211], v[10:13]
	v_mfma_f32_16x16x32_bf16 v[62:65], v[154:157], v[188:191], v[62:65]
	v_mfma_f32_16x16x32_bf16 v[58:61], v[180:183], v[188:191], v[58:61]
	v_mfma_f32_16x16x32_bf16 v[46:49], v[154:157], v[196:199], v[46:49]
	v_mfma_f32_16x16x32_bf16 v[42:45], v[180:183], v[196:199], v[42:45]
	v_mfma_f32_16x16x32_bf16 v[30:33], v[154:157], v[204:207], v[30:33]
	v_mfma_f32_16x16x32_bf16 v[26:29], v[180:183], v[204:207], v[26:29]
	v_mfma_f32_16x16x32_bf16 v[14:17], v[154:157], v[212:215], v[14:17]
	v_mfma_f32_16x16x32_bf16 v[10:13], v[180:183], v[212:215], v[10:13]
	s_setprio 0
	s_barrier
; #define PG8_STAGE(bufoff, gbase) do { _Pragma("unroll") for (int _i = 0; _i < 2; ++_i) \
;     __builtin_amdgcn_global_load_lds((const unsigned*)((const char*)(gbase) + voff[_i]), (LAS unsigned*)(lds + (bufoff) + ldsw + _i * 8192), 16, 0, 0); } while (0)
; #define PG8_LDA(dst, b, h) do { _Pragma("unroll") for (int m = 0; m < 4; ++m) _Pragma("unroll") for (int k = 0; k < 2; ++k) dst[m][k] = *(const LAS bf16x8*)(lds + PG8_SA(b, h) + aoff + m * 2048 + k * 1024); } while (0)
; #define PG8_LDB(dst, b, h) do { _Pragma("unroll") for (int n = 0; n < 2; ++n) _Pragma("unroll") for (int k = 0; k < 2; ++k) dst[n][k] = *(const LAS bf16x8*)(lds + PG8_SB(b, h) + boff + n * 2048 + k * 1024); } while (0)
; #define PG8_MMA(ai, bj, At, Bt_) do { __builtin_amdgcn_s_setprio(1); _Pragma("unroll") for (int m = 0; m < 4; ++m) _Pragma("unroll") for (int n = 0; n < 2; ++n) _Pragma("unroll") for (int k = 0; k < 2; ++k) \
;     acc[ai][bj][m][n] = __builtin_amdgcn_mfma_f32_16x16x32_bf16(Bt_[n][k], At[m][k], acc[ai][bj][m][n], 0, 0, 0); __builtin_amdgcn_s_setprio(0); } while (0)
; #define PG8_WAIT_V(n) asm volatile("s_waitcnt vmcnt(" #n ")" ::: "memory")
; #define PG8_WAIT_L(n) asm volatile("s_waitcnt lgkmcnt(" #n ")" ::: "memory")
; #define PG8_BAR __builtin_amdgcn_s_barrier()
; #define PG8_SCHED __builtin_amdgcn_sched_barrier(0)
; template <int EPI>
; __device__ __forceinline__ void gemm_phase(KP P, const bfu* __restrict__ A, const bfu* __restrict__ Bt, int K, int ntn, char* smem, const int wv) {
;     ...
;       PG8_STAGE(PG8_SB(0, 1), b2 + hstep);
;       PG8_WAIT_V(6); PG8_BAR; PG8_MMA(1, 1, At, B1); PG8_BAR;
;       PG8_LDB(B0, 1, 0); PG8_SCHED; PG8_LDA(At, 1, 0); PG8_STAGE(PG8_SA(0, 1), a2 + hstep);
;       PG8_WAIT_L(8); PG8_BAR; PG8_WAIT_L(0); PG8_MMA(0, 0, At, B0); PG8_BAR; PG8_SCHED;
;       PG8_LDB(B1, 1, 1); PG8_STAGE(PG8_SB(1, 0), b3);
;       PG8_BAR; PG8_WAIT_L(0); PG8_MMA(0, 1, At, B1); PG8_BAR;
;       PG8_LDA(At, 1, 1); PG8_STAGE(PG8_SA(1, 0), a3);
;       PG8_BAR; PG8_WAIT_L(0); PG8_MMA(1, 0, At, B0); PG8_BAR; PG8_SCHED;
;       PG8_STAGE(PG8_SB(1, 1), b3 + hstep);
	s_add_u32 s80, s24, 0x40000
	s_addc_u32 s81, s25, 0
	s_mov_b32 m0, s41
	v_lshl_add_u64 v[150:151], s[80:81], 0, v[130:131]
	global_load_lds_dwordx4 v[150:151], off
	v_lshl_add_u64 v[150:151], s[80:81], 0, v[132:133]
	s_mov_b32 m0, s42
	s_nop 0
	global_load_lds_dwordx4 v[150:151], off
	s_waitcnt vmcnt(6)
	s_barrier
	s_setprio 1
	v_mfma_f32_16x16x32_bf16 v[54:57], v[216:219], v[184:187], v[54:57]
	v_mfma_f32_16x16x32_bf16 v[50:53], v[224:227], v[184:187], v[50:53]
	v_mfma_f32_16x16x32_bf16 v[38:41], v[216:219], v[192:195], v[38:41]
	v_mfma_f32_16x16x32_bf16 v[34:37], v[224:227], v[192:195], v[34:37]
	v_mfma_f32_16x16x32_bf16 v[22:25], v[216:219], v[200:203], v[22:25]
	v_mfma_f32_16x16x32_bf16 v[18:21], v[224:227], v[200:203], v[18:21]
	v_mfma_f32_16x16x32_bf16 v[6:9], v[216:219], v[208:211], v[6:9]
	v_mfma_f32_16x16x32_bf16 v[2:5], v[224:227], v[208:211], v[2:5]
	v_mfma_f32_16x16x32_bf16 v[54:57], v[220:223], v[188:191], v[54:57]
	v_mfma_f32_16x16x32_bf16 v[50:53], v[228:231], v[188:191], v[50:53]
	v_mfma_f32_16x16x32_bf16 v[38:41], v[220:223], v[196:199], v[38:41]
	v_mfma_f32_16x16x32_bf16 v[34:37], v[228:231], v[196:199], v[34:37]
	v_mfma_f32_16x16x32_bf16 v[22:25], v[220:223], v[204:207], v[22:25]
	v_mfma_f32_16x16x32_bf16 v[18:21], v[228:231], v[204:207], v[18:21]
	v_mfma_f32_16x16x32_bf16 v[6:9], v[220:223], v[212:215], v[6:9]
	v_mfma_f32_16x16x32_bf16 v[2:5], v[228:231], v[212:215], v[2:5]
	s_setprio 0
	v_add_u32_e32 v0, s45, v144
	s_barrier
	ds_read_b128 v[150:153], v0
	ds_read_b128 v[154:157], v0 offset:1024
	ds_read_b128 v[158:161], v0 offset:2048
	ds_read_b128 v[180:183], v0 offset:3072
	s_add_u32 s26, s26, 0x40000
	s_addc_u32 s27, s27, 0
	s_mov_b32 m0, s43
	v_lshl_add_u64 v[216:217], s[26:27], 0, v[130:131]
	ds_read_b128 v[184:187], v145 offset:32768
	ds_read_b128 v[188:191], v145 offset:33792
	ds_read_b128 v[192:195], v145 offset:34816
	ds_read_b128 v[196:199], v145 offset:35840
	ds_read_b128 v[200:203], v145 offset:36864
	ds_read_b128 v[204:207], v145 offset:37888
	ds_read_b128 v[208:211], v145 offset:38912
	ds_read_b128 v[212:215], v145 offset:39936
	global_load_lds_dwordx4 v[216:217], off
	v_lshl_add_u64 v[216:217], s[26:27], 0, v[132:133]
	s_mov_b32 m0, s44
	s_nop 0
	global_load_lds_dwordx4 v[216:217], off
	s_waitcnt lgkmcnt(8)
	s_barrier
	s_waitcnt lgkmcnt(0)
	s_setprio 1
	s_waitcnt lgkmcnt(0)
	v_mfma_f32_16x16x32_bf16 v[126:129], v[150:153], v[184:187], v[126:129]
	v_mfma_f32_16x16x32_bf16 v[122:125], v[158:161], v[184:187], v[122:125]
	v_mfma_f32_16x16x32_bf16 v[110:113], v[150:153], v[192:195], v[110:113]
	v_mfma_f32_16x16x32_bf16 v[106:109], v[158:161], v[192:195], v[106:109]
	v_mfma_f32_16x16x32_bf16 v[94:97], v[150:153], v[200:203], v[94:97]
	v_mfma_f32_16x16x32_bf16 v[90:93], v[158:161], v[200:203], v[90:93]
	v_mfma_f32_16x16x32_bf16 v[78:81], v[150:153], v[208:211], v[78:81]
	v_mfma_f32_16x16x32_bf16 v[74:77], v[158:161], v[208:211], v[74:77]
	v_mfma_f32_16x16x32_bf16 v[126:129], v[154:157], v[188:191], v[126:129]
	v_mfma_f32_16x16x32_bf16 v[122:125], v[180:183], v[188:191], v[122:125]
	v_mfma_f32_16x16x32_bf16 v[110:113], v[154:157], v[196:199], v[110:113]
	v_mfma_f32_16x16x32_bf16 v[106:109], v[180:183], v[196:199], v[106:109]
	v_mfma_f32_16x16x32_bf16 v[94:97], v[154:157], v[204:207], v[94:97]
	v_mfma_f32_16x16x32_bf16 v[90:93], v[180:183], v[204:207], v[90:93]
	v_mfma_f32_16x16x32_bf16 v[78:81], v[154:157], v[212:215], v[78:81]
	v_mfma_f32_16x16x32_bf16 v[74:77], v[180:183], v[212:215], v[74:77]
	s_setprio 0
	s_barrier
	s_mov_b32 m0, s46
	v_add_u32_e32 v0, s50, v144
	v_lshl_add_u64 v[162:163], v[162:163], 0, s[90:91]
	ds_read_b128 v[216:219], v0
	ds_read_b128 v[220:223], v0 offset:1024
	ds_read_b128 v[224:227], v0 offset:2048
	ds_read_b128 v[228:231], v0 offset:3072
	global_load_lds_dwordx4 v[162:163], off
	v_lshl_add_u64 v[162:163], v[232:233], 0, s[90:91]
	s_mov_b32 m0, s47
	s_nop 0
	global_load_lds_dwordx4 v[162:163], off
	s_barrier
	s_waitcnt lgkmcnt(0)
	s_setprio 1
	s_waitcnt lgkmcnt(0)
	v_mfma_f32_16x16x32_bf16 v[118:121], v[216:219], v[184:187], v[118:121]
	v_mfma_f32_16x16x32_bf16 v[114:117], v[224:227], v[184:187], v[114:117]
	v_mfma_f32_16x16x32_bf16 v[102:105], v[216:219], v[192:195], v[102:105]
	v_mfma_f32_16x16x32_bf16 v[98:101], v[224:227], v[192:195], v[98:101]
	v_mfma_f32_16x16x32_bf16 v[86:89], v[216:219], v[200:203], v[86:89]
	v_mfma_f32_16x16x32_bf16 v[82:85], v[224:227], v[200:203], v[82:85]
	v_mfma_f32_16x16x32_bf16 v[70:73], v[216:219], v[208:211], v[70:73]
	v_mfma_f32_16x16x32_bf16 v[66:69], v[224:227], v[208:211], v[66:69]
	v_mfma_f32_16x16x32_bf16 v[118:121], v[220:223], v[188:191], v[118:121]
	v_mfma_f32_16x16x32_bf16 v[114:117], v[228:231], v[188:191], v[114:117]
	v_mfma_f32_16x16x32_bf16 v[102:105], v[220:223], v[196:199], v[102:105]
	v_mfma_f32_16x16x32_bf16 v[98:101], v[228:231], v[196:199], v[98:101]
	v_mfma_f32_16x16x32_bf16 v[86:89], v[220:223], v[204:207], v[86:89]
	v_mfma_f32_16x16x32_bf16 v[82:85], v[228:231], v[204:207], v[82:85]
	v_mfma_f32_16x16x32_bf16 v[70:73], v[220:223], v[212:215], v[70:73]
	v_mfma_f32_16x16x32_bf16 v[66:69], v[228:231], v[212:215], v[66:69]
	s_setprio 0
	s_mov_b32 m0, s48
	v_lshl_add_u64 v[162:163], v[234:235], 0, s[90:91]
	s_barrier
	ds_read_b128 v[184:187], v145 offset:49152
	ds_read_b128 v[188:191], v145 offset:50176
	ds_read_b128 v[192:195], v145 offset:51200
	ds_read_b128 v[196:199], v145 offset:52224
	ds_read_b128 v[200:203], v145 offset:53248
	ds_read_b128 v[204:207], v145 offset:54272
	ds_read_b128 v[208:211], v145 offset:55296
	ds_read_b128 v[212:215], v145 offset:56320
	global_load_lds_dwordx4 v[162:163], off
	v_lshl_add_u64 v[162:163], v[236:237], 0, s[90:91]
	s_mov_b32 m0, s49
	s_nop 0
	global_load_lds_dwordx4 v[162:163], off
	s_barrier
; __device__ __forceinline__ float silu_f(float x) { return x * __builtin_amdgcn_rcpf(1.f + __expf(-x)); }
; #define PG8_STAGE(bufoff, gbase) do { _Pragma("unroll") for (int _i = 0; _i < 2; ++_i) \
;     __builtin_amdgcn_global_load_lds((const unsigned*)((const char*)(gbase) + voff[_i]), (LAS unsigned*)(lds + (bufoff) + ldsw + _i * 8192), 16, 0, 0); } while (0)
; #define PG8_MMA(ai, bj, At, Bt_) do { __builtin_amdgcn_s_setprio(1); _Pragma("unroll") for (int m = 0; m < 4; ++m) _Pragma("unroll") for (int n = 0; n < 2; ++n) _Pragma("unroll") for (int k = 0; k < 2; ++k) \
;     acc[ai][bj][m][n] = __builtin_amdgcn_mfma_f32_16x16x32_bf16(Bt_[n][k], At[m][k], acc[ai][bj][m][n], 0, 0, 0); __builtin_amdgcn_s_setprio(0); } while (0)
; #define PG8_WAIT_V(n) asm volatile("s_waitcnt vmcnt(" #n ")" ::: "memory")
; #define PG8_WAIT_L(n) asm volatile("s_waitcnt lgkmcnt(" #n ")" ::: "memory")
; #define PG8_BAR __builtin_amdgcn_s_barrier()
; #define PG8_SCHED __builtin_amdgcn_sched_barrier(0)
; template <int EPI>
; __device__ __forceinline__ void gemm_epilogue(KP P, f32x4 (&acc)[2][2][4][2], int brow, int bcol, int wr, int wc, int fr_, int fq_, const float* sRu) {
;     ...
;   } else if (EPI == EPI_GU) {
;     bfu* hb = (bfu*)(P->ws + WS_BIG) + (size_t)brow * DFF + (bcol >> 1);
; #pragma unroll
;     for (int ai = 0; ai < 2; ++ai)
; #pragma unroll
;       for (int m = 0; m < 4; ++m) {
;         __builtin_amdgcn_sched_barrier(0);
;         unsigned o = (lrow0 + ai * 128 + m * 16) * DFF + wc * 16 + fq * 4;
; #pragma unroll
;         for (int bj = 0; bj < 2; ++bj) {
;           f32x4 g = acc[ai][bj][m][0], u = acc[ai][bj][m][1];
;           uint2 pk;
;           pk.x = cvt_pk_bf16(silu_f(g[0]) * u[0], silu_f(g[1]) * u[1]);
;           pk.y = cvt_pk_bf16(silu_f(g[2]) * u[2], silu_f(g[3]) * u[3]);
;           *(uint2*)(hb + o + bj * 64) = pk;
;         }
;       }
; template <int EPI>
; __device__ __forceinline__ void gemm_phase(KP P, const bfu* __restrict__ A, const bfu* __restrict__ Bt, int K, int ntn, char* smem, const int wv) {
;     ...
;       PG8_BAR; PG8_WAIT_L(0); PG8_MMA(1, 0, At, B0); PG8_BAR; PG8_SCHED;
;       PG8_STAGE(PG8_SB(1, 1), b3 + hstep);
;       PG8_WAIT_V(6); PG8_BAR; PG8_MMA(1, 1, At, B1); PG8_BAR;
;     }
;     gemm_epilogue<EPI>(P, acc, cpm * 256, cpn * 256, wr, wc, fr, fq, sRu);
	s_waitcnt lgkmcnt(0)
	s_setprio 1
	s_waitcnt lgkmcnt(0)
	v_mfma_f32_16x16x32_bf16 v[62:65], v[150:153], v[184:187], v[62:65]
	v_mfma_f32_16x16x32_bf16 v[58:61], v[158:161], v[184:187], v[58:61]
	v_mfma_f32_16x16x32_bf16 v[46:49], v[150:153], v[192:195], v[46:49]
	v_mfma_f32_16x16x32_bf16 v[42:45], v[158:161], v[192:195], v[42:45]
	v_mfma_f32_16x16x32_bf16 v[30:33], v[150:153], v[200:203], v[30:33]
	v_mfma_f32_16x16x32_bf16 v[26:29], v[158:161], v[200:203], v[26:29]
	v_mfma_f32_16x16x32_bf16 v[14:17], v[150:153], v[208:211], v[14:17]
	v_mfma_f32_16x16x32_bf16 v[10:13], v[158:161], v[208:211], v[10:13]
	v_mfma_f32_16x16x32_bf16 v[62:65], v[154:157], v[188:191], v[62:65]
	v_mfma_f32_16x16x32_bf16 v[58:61], v[180:183], v[188:191], v[58:61]
	v_mfma_f32_16x16x32_bf16 v[46:49], v[154:157], v[196:199], v[46:49]
	v_mfma_f32_16x16x32_bf16 v[42:45], v[180:183], v[196:199], v[42:45]
	v_mfma_f32_16x16x32_bf16 v[30:33], v[154:157], v[204:207], v[30:33]
	v_mfma_f32_16x16x32_bf16 v[26:29], v[180:183], v[204:207], v[26:29]
	v_mfma_f32_16x16x32_bf16 v[14:17], v[154:157], v[212:215], v[14:17]
	v_mfma_f32_16x16x32_bf16 v[10:13], v[180:183], v[212:215], v[10:13]
	s_setprio 0
	s_barrier
	s_add_u32 s24, s24, 0x40080
	s_addc_u32 s25, s25, 0
	s_mov_b32 m0, s51
	v_lshl_add_u64 v[150:151], s[24:25], 0, v[130:131]
	global_load_lds_dwordx4 v[150:151], off
	v_lshl_add_u64 v[150:151], s[24:25], 0, v[132:133]
	s_mov_b32 m0, s52
	s_nop 0
	global_load_lds_dwordx4 v[150:151], off
	s_waitcnt vmcnt(6)
	s_barrier
	s_setprio 1
	v_mfma_f32_16x16x32_bf16 v[54:57], v[216:219], v[184:187], v[54:57]
	v_mfma_f32_16x16x32_bf16 v[50:53], v[224:227], v[184:187], v[50:53]
	v_mfma_f32_16x16x32_bf16 v[38:41], v[216:219], v[192:195], v[38:41]
	v_mfma_f32_16x16x32_bf16 v[34:37], v[224:227], v[192:195], v[34:37]
	v_mfma_f32_16x16x32_bf16 v[22:25], v[216:219], v[200:203], v[22:25]
	v_mfma_f32_16x16x32_bf16 v[18:21], v[224:227], v[200:203], v[18:21]
	v_mfma_f32_16x16x32_bf16 v[6:9], v[216:219], v[208:211], v[6:9]
	v_mfma_f32_16x16x32_bf16 v[2:5], v[224:227], v[208:211], v[2:5]
	v_mfma_f32_16x16x32_bf16 v[54:57], v[220:223], v[188:191], v[54:57]
	v_mfma_f32_16x16x32_bf16 v[50:53], v[228:231], v[188:191], v[50:53]
	v_mfma_f32_16x16x32_bf16 v[38:41], v[220:223], v[196:199], v[38:41]
	v_mfma_f32_16x16x32_bf16 v[34:37], v[228:231], v[196:199], v[34:37]
	v_mfma_f32_16x16x32_bf16 v[22:25], v[220:223], v[204:207], v[22:25]
	v_mfma_f32_16x16x32_bf16 v[18:21], v[228:231], v[204:207], v[18:21]
	v_mfma_f32_16x16x32_bf16 v[6:9], v[220:223], v[212:215], v[6:9]
	v_mfma_f32_16x16x32_bf16 v[2:5], v[228:231], v[212:215], v[2:5]
	s_setprio 0
	s_add_i32 s79, s79, 2
	s_add_u32 s22, s22, 0x100
	s_addc_u32 s23, s23, 0
	s_cmp_gt_u32 s79, 13
	s_barrier
	s_cbranch_scc0 .LBB0_264
	s_lshl_b32 s11, s20, 8
	s_mul_i32 s15, s20, 0x160000
	s_mul_hi_i32 s11, s11, 0x1600
	s_add_u32 s15, s60, s15
	s_addc_u32 s11, s62, s11
	s_lshl_b32 s20, s21, 7
	s_ashr_i32 s21, s20, 31
	s_lshl_b64 s[20:21], s[20:21], 1
	v_mov_b32_e32 v0, v142
	v_mov_b32_e32 v138, v143
	s_add_u32 s20, s15, s20
	s_addc_u32 s21, s11, s21
	v_add_u32_e32 v0, s94, v0
	v_lshlrev_b32_e32 v138, 2, v138
	v_and_b32_e32 v206, 1, v143
	v_mul_u32_u24_e32 v206, 60, v206
	v_add_u32_e32 v138, v138, v206
	s_movk_i32 s11, 0xb00
	v_mul_lo_u32 v0, v0, s11
	v_readlane_b32 s11, v241, 24
	v_mov_b32_e32 v204, 0xbfb8aa3b
	v_mov_b32_e32 v205, 0xbfb8aa3b
	s_nop 0
	v_add3_u32 v0, v138, s11, v0
	v_lshl_add_u64 v[200:201], v[0:1], 1, s[20:21]
	v_pk_mul_f32 v[184:185], v[204:205], v[126:127]
	v_pk_mul_f32 v[188:189], v[204:205], v[118:119]
	v_pk_mul_f32 v[186:187], v[204:205], v[128:129]
	v_pk_mul_f32 v[190:191], v[204:205], v[120:121]
	v_exp_f32_e32 v184, v184
	v_exp_f32_e32 v188, v188
	v_exp_f32_e32 v185, v185
	v_exp_f32_e32 v189, v189
	v_exp_f32_e32 v186, v186
	v_exp_f32_e32 v190, v190
	v_exp_f32_e32 v187, v187
	v_exp_f32_e32 v191, v191
	v_pk_add_f32 v[184:185], v[184:185], 1.0 op_sel_hi:[1,0]
	v_pk_add_f32 v[188:189], v[188:189], 1.0 op_sel_hi:[1,0]
	v_pk_add_f32 v[186:187], v[186:187], 1.0 op_sel_hi:[1,0]
	v_pk_add_f32 v[190:191], v[190:191], 1.0 op_sel_hi:[1,0]
	v_rcp_f32_e32 v184, v184
	v_rcp_f32_e32 v188, v188
	v_rcp_f32_e32 v185, v185
	v_rcp_f32_e32 v189, v189
	v_rcp_f32_e32 v186, v186
	v_rcp_f32_e32 v190, v190
	v_rcp_f32_e32 v187, v187
	v_rcp_f32_e32 v191, v191
	v_pk_mul_f32 v[184:185], v[126:127], v[184:185]
	v_pk_mul_f32 v[188:189], v[118:119], v[188:189]
	v_pk_mul_f32 v[186:187], v[128:129], v[186:187]
	v_pk_mul_f32 v[190:191], v[120:121], v[190:191]
	v_pk_mul_f32 v[184:185], v[122:123], v[184:185]
	v_pk_mul_f32 v[188:189], v[114:115], v[188:189]
	v_pk_mul_f32 v[186:187], v[124:125], v[186:187]
	v_pk_mul_f32 v[190:191], v[116:117], v[190:191]
	v_cvt_pk_bf16_f32 v192, v184, v185
	v_cvt_pk_bf16_f32 v194, v188, v189
	v_cvt_pk_bf16_f32 v193, v186, v187
	v_cvt_pk_bf16_f32 v195, v190, v191
	s_nop 1
	v_permlane16_swap_b32_e32 v192, v194
	v_permlane16_swap_b32_e32 v193, v195
	global_store_dwordx4 v[200:201], v[192:195], off
	v_add_u32_e32 v202, 0xb000, v0
	v_mov_b32_e32 v203, v1
	v_lshl_add_u64 v[202:203], v[202:203], 1, s[20:21]
	v_pk_mul_f32 v[184:185], v[204:205], v[110:111]
	v_pk_mul_f32 v[188:189], v[204:205], v[102:103]
	v_pk_mul_f32 v[186:187], v[204:205], v[112:113]
	v_pk_mul_f32 v[190:191], v[204:205], v[104:105]
	v_exp_f32_e32 v184, v184
	v_exp_f32_e32 v188, v188
	v_exp_f32_e32 v185, v185
	v_exp_f32_e32 v189, v189
	v_exp_f32_e32 v186, v186
	v_exp_f32_e32 v190, v190
	v_exp_f32_e32 v187, v187
	v_exp_f32_e32 v191, v191
	v_pk_add_f32 v[184:185], v[184:185], 1.0 op_sel_hi:[1,0]
	v_pk_add_f32 v[188:189], v[188:189], 1.0 op_sel_hi:[1,0]
	v_pk_add_f32 v[186:187], v[186:187], 1.0 op_sel_hi:[1,0]
; __device__ __forceinline__ float silu_f(float x) { return x * __builtin_amdgcn_rcpf(1.f + __expf(-x)); }
; template <int EPI>
; __device__ __forceinline__ void gemm_epilogue(KP P, f32x4 (&acc)[2][2][4][2], int brow, int bcol, int wr, int wc, int fr_, int fq_, const float* sRu) {
;     ...
;   } else if (EPI == EPI_GU) {
;     bfu* hb = (bfu*)(P->ws + WS_BIG) + (size_t)brow * DFF + (bcol >> 1);
; #pragma unroll
;     for (int ai = 0; ai < 2; ++ai)
; #pragma unroll
;       for (int m = 0; m < 4; ++m) {
;         __builtin_amdgcn_sched_barrier(0);
;         unsigned o = (lrow0 + ai * 128 + m * 16) * DFF + wc * 16 + fq * 4;
; #pragma unroll
;         for (int bj = 0; bj < 2; ++bj) {
;           f32x4 g = acc[ai][bj][m][0], u = acc[ai][bj][m][1];
;           uint2 pk;
;           pk.x = cvt_pk_bf16(silu_f(g[0]) * u[0], silu_f(g[1]) * u[1]);
;           pk.y = cvt_pk_bf16(silu_f(g[2]) * u[2], silu_f(g[3]) * u[3]);
;           *(uint2*)(hb + o + bj * 64) = pk;
;         }
;       }
	v_pk_add_f32 v[190:191], v[190:191], 1.0 op_sel_hi:[1,0]
	v_rcp_f32_e32 v184, v184
	v_rcp_f32_e32 v188, v188
	v_rcp_f32_e32 v185, v185
	v_rcp_f32_e32 v189, v189
	v_rcp_f32_e32 v186, v186
	v_rcp_f32_e32 v190, v190
	v_rcp_f32_e32 v187, v187
	v_rcp_f32_e32 v191, v191
	v_pk_mul_f32 v[184:185], v[110:111], v[184:185]
	v_pk_mul_f32 v[188:189], v[102:103], v[188:189]
	v_pk_mul_f32 v[186:187], v[112:113], v[186:187]
	v_pk_mul_f32 v[190:191], v[104:105], v[190:191]
	v_pk_mul_f32 v[184:185], v[106:107], v[184:185]
	v_pk_mul_f32 v[188:189], v[98:99], v[188:189]
	v_pk_mul_f32 v[186:187], v[108:109], v[186:187]
	v_pk_mul_f32 v[190:191], v[100:101], v[190:191]
	v_cvt_pk_bf16_f32 v196, v184, v185
	v_cvt_pk_bf16_f32 v198, v188, v189
	v_cvt_pk_bf16_f32 v197, v186, v187
	v_cvt_pk_bf16_f32 v199, v190, v191
	s_nop 1
	v_permlane16_swap_b32_e32 v196, v198
	v_permlane16_swap_b32_e32 v197, v199
	global_store_dwordx4 v[202:203], v[196:199], off
	v_add_u32_e32 v200, 0x16000, v0
	v_mov_b32_e32 v201, v1
	v_lshl_add_u64 v[200:201], v[200:201], 1, s[20:21]
	v_pk_mul_f32 v[184:185], v[204:205], v[94:95]
	v_pk_mul_f32 v[188:189], v[204:205], v[86:87]
	v_pk_mul_f32 v[186:187], v[204:205], v[96:97]
	v_pk_mul_f32 v[190:191], v[204:205], v[88:89]
	v_exp_f32_e32 v184, v184
	v_exp_f32_e32 v188, v188
	v_exp_f32_e32 v185, v185
	v_exp_f32_e32 v189, v189
	v_exp_f32_e32 v186, v186
	v_exp_f32_e32 v190, v190
	v_exp_f32_e32 v187, v187
	v_exp_f32_e32 v191, v191
	v_pk_add_f32 v[184:185], v[184:185], 1.0 op_sel_hi:[1,0]
	v_pk_add_f32 v[188:189], v[188:189], 1.0 op_sel_hi:[1,0]
	v_pk_add_f32 v[186:187], v[186:187], 1.0 op_sel_hi:[1,0]
	v_pk_add_f32 v[190:191], v[190:191], 1.0 op_sel_hi:[1,0]
	v_rcp_f32_e32 v184, v184
	v_rcp_f32_e32 v188, v188
	v_rcp_f32_e32 v185, v185
	v_rcp_f32_e32 v189, v189
	v_rcp_f32_e32 v186, v186
	v_rcp_f32_e32 v190, v190
	v_rcp_f32_e32 v187, v187
	v_rcp_f32_e32 v191, v191
	v_pk_mul_f32 v[184:185], v[94:95], v[184:185]
	v_pk_mul_f32 v[188:189], v[86:87], v[188:189]
	v_pk_mul_f32 v[186:187], v[96:97], v[186:187]
	v_pk_mul_f32 v[190:191], v[88:89], v[190:191]
	v_pk_mul_f32 v[184:185], v[90:91], v[184:185]
	v_pk_mul_f32 v[188:189], v[82:83], v[188:189]
	v_pk_mul_f32 v[186:187], v[92:93], v[186:187]
	v_pk_mul_f32 v[190:191], v[84:85], v[190:191]
	v_cvt_pk_bf16_f32 v192, v184, v185
	v_cvt_pk_bf16_f32 v194, v188, v189
	v_cvt_pk_bf16_f32 v193, v186, v187
	v_cvt_pk_bf16_f32 v195, v190, v191
	s_nop 1
	v_permlane16_swap_b32_e32 v192, v194
	v_permlane16_swap_b32_e32 v193, v195
	global_store_dwordx4 v[200:201], v[192:195], off
	v_add_u32_e32 v202, 0x21000, v0
	v_mov_b32_e32 v203, v1
	v_lshl_add_u64 v[202:203], v[202:203], 1, s[20:21]
	v_pk_mul_f32 v[184:185], v[204:205], v[78:79]
	v_pk_mul_f32 v[188:189], v[204:205], v[70:71]
	v_pk_mul_f32 v[186:187], v[204:205], v[80:81]
	v_pk_mul_f32 v[190:191], v[204:205], v[72:73]
	v_exp_f32_e32 v184, v184
	v_exp_f32_e32 v188, v188
	v_exp_f32_e32 v185, v185
	v_exp_f32_e32 v189, v189
	v_exp_f32_e32 v186, v186
	v_exp_f32_e32 v190, v190
	v_exp_f32_e32 v187, v187
	v_exp_f32_e32 v191, v191
	v_pk_add_f32 v[184:185], v[184:185], 1.0 op_sel_hi:[1,0]
	v_pk_add_f32 v[188:189], v[188:189], 1.0 op_sel_hi:[1,0]
	v_pk_add_f32 v[186:187], v[186:187], 1.0 op_sel_hi:[1,0]
	v_pk_add_f32 v[190:191], v[190:191], 1.0 op_sel_hi:[1,0]
	v_rcp_f32_e32 v184, v184
	v_rcp_f32_e32 v188, v188
	v_rcp_f32_e32 v185, v185
	v_rcp_f32_e32 v189, v189
	v_rcp_f32_e32 v186, v186
	v_rcp_f32_e32 v190, v190
	v_rcp_f32_e32 v187, v187
	v_rcp_f32_e32 v191, v191
	v_pk_mul_f32 v[184:185], v[78:79], v[184:185]
	v_pk_mul_f32 v[188:189], v[70:71], v[188:189]
	v_pk_mul_f32 v[186:187], v[80:81], v[186:187]
	v_pk_mul_f32 v[190:191], v[72:73], v[190:191]
	v_pk_mul_f32 v[184:185], v[74:75], v[184:185]
	v_pk_mul_f32 v[188:189], v[66:67], v[188:189]
	v_pk_mul_f32 v[186:187], v[76:77], v[186:187]
	v_pk_mul_f32 v[190:191], v[68:69], v[190:191]
	v_cvt_pk_bf16_f32 v196, v184, v185
	v_cvt_pk_bf16_f32 v198, v188, v189
	v_cvt_pk_bf16_f32 v197, v186, v187
	v_cvt_pk_bf16_f32 v199, v190, v191
	s_nop 1
	v_permlane16_swap_b32_e32 v196, v198
	v_permlane16_swap_b32_e32 v197, v199
	global_store_dwordx4 v[202:203], v[196:199], off
	v_add_u32_e32 v200, 0x58000, v0
	v_mov_b32_e32 v201, v1
	v_lshl_add_u64 v[200:201], v[200:201], 1, s[20:21]
	v_pk_mul_f32 v[184:185], v[204:205], v[62:63]
	v_pk_mul_f32 v[188:189], v[204:205], v[54:55]
	v_pk_mul_f32 v[186:187], v[204:205], v[64:65]
	v_pk_mul_f32 v[190:191], v[204:205], v[56:57]
	v_exp_f32_e32 v184, v184
	v_exp_f32_e32 v188, v188
	v_exp_f32_e32 v185, v185
	v_exp_f32_e32 v189, v189
	v_exp_f32_e32 v186, v186
	v_exp_f32_e32 v190, v190
	v_exp_f32_e32 v187, v187
	v_exp_f32_e32 v191, v191
	v_pk_add_f32 v[184:185], v[184:185], 1.0 op_sel_hi:[1,0]
	v_pk_add_f32 v[188:189], v[188:189], 1.0 op_sel_hi:[1,0]
	v_pk_add_f32 v[186:187], v[186:187], 1.0 op_sel_hi:[1,0]
	v_pk_add_f32 v[190:191], v[190:191], 1.0 op_sel_hi:[1,0]
	v_rcp_f32_e32 v184, v184
	v_rcp_f32_e32 v188, v188
	v_rcp_f32_e32 v185, v185
	v_rcp_f32_e32 v189, v189
	v_rcp_f32_e32 v186, v186
	v_rcp_f32_e32 v190, v190
	v_rcp_f32_e32 v187, v187
	v_rcp_f32_e32 v191, v191
	v_pk_mul_f32 v[184:185], v[62:63], v[184:185]
	v_pk_mul_f32 v[188:189], v[54:55], v[188:189]
	v_pk_mul_f32 v[186:187], v[64:65], v[186:187]
	v_pk_mul_f32 v[190:191], v[56:57], v[190:191]
	v_pk_mul_f32 v[184:185], v[58:59], v[184:185]
	v_pk_mul_f32 v[188:189], v[50:51], v[188:189]
	v_pk_mul_f32 v[186:187], v[60:61], v[186:187]
; __device__ __forceinline__ float silu_f(float x) { return x * __builtin_amdgcn_rcpf(1.f + __expf(-x)); }
; #define PG8_WAIT_V(n) asm volatile("s_waitcnt vmcnt(" #n ")" ::: "memory")
; #define PG8_BAR __builtin_amdgcn_s_barrier()
; template <int EPI>
; __device__ __forceinline__ void gemm_epilogue(KP P, f32x4 (&acc)[2][2][4][2], int brow, int bcol, int wr, int wc, int fr_, int fq_, const float* sRu) {
;     ...
;   } else if (EPI == EPI_GU) {
;     bfu* hb = (bfu*)(P->ws + WS_BIG) + (size_t)brow * DFF + (bcol >> 1);
; #pragma unroll
;     for (int ai = 0; ai < 2; ++ai)
; #pragma unroll
;       for (int m = 0; m < 4; ++m) {
;         __builtin_amdgcn_sched_barrier(0);
;         unsigned o = (lrow0 + ai * 128 + m * 16) * DFF + wc * 16 + fq * 4;
; #pragma unroll
;         for (int bj = 0; bj < 2; ++bj) {
;           f32x4 g = acc[ai][bj][m][0], u = acc[ai][bj][m][1];
;           uint2 pk;
;           pk.x = cvt_pk_bf16(silu_f(g[0]) * u[0], silu_f(g[1]) * u[1]);
;           pk.y = cvt_pk_bf16(silu_f(g[2]) * u[2], silu_f(g[3]) * u[3]);
;           *(uint2*)(hb + o + bj * 64) = pk;
;         }
;       }
; template <int EPI>
; __device__ __forceinline__ void gemm_phase(KP P, const bfu* __restrict__ A, const bfu* __restrict__ Bt, int K, int ntn, char* smem, const int wv) {
;     ...
;     gemm_epilogue<EPI>(P, acc, cpm * 256, cpn * 256, wr, wc, fr, fq, sRu);
;     if (!has_next) break;
;     sRu += 256;
;     gemm_acc_init<EPI>(P, acc, npm * 256, npn * 256, wr, wc, fr, fq, sRu);
;     ctile = ntile; cpm = npm; cpn = npn; cA = nA; cB = nB;
;   }
;   PG8_WAIT_V(0);
;   if (wr == 0) PG8_BAR;
;   PG8_BAR;
	v_pk_mul_f32 v[190:191], v[52:53], v[190:191]
	v_cvt_pk_bf16_f32 v192, v184, v185
	v_cvt_pk_bf16_f32 v194, v188, v189
	v_cvt_pk_bf16_f32 v193, v186, v187
	v_cvt_pk_bf16_f32 v195, v190, v191
	s_nop 1
	v_permlane16_swap_b32_e32 v192, v194
	v_permlane16_swap_b32_e32 v193, v195
	global_store_dwordx4 v[200:201], v[192:195], off
	v_add_u32_e32 v202, 0x63000, v0
	v_mov_b32_e32 v203, v1
	v_lshl_add_u64 v[202:203], v[202:203], 1, s[20:21]
	v_pk_mul_f32 v[184:185], v[204:205], v[46:47]
	v_pk_mul_f32 v[188:189], v[204:205], v[38:39]
	v_pk_mul_f32 v[186:187], v[204:205], v[48:49]
	v_pk_mul_f32 v[190:191], v[204:205], v[40:41]
	v_exp_f32_e32 v184, v184
	v_exp_f32_e32 v188, v188
	v_exp_f32_e32 v185, v185
	v_exp_f32_e32 v189, v189
	v_exp_f32_e32 v186, v186
	v_exp_f32_e32 v190, v190
	v_exp_f32_e32 v187, v187
	v_exp_f32_e32 v191, v191
	v_pk_add_f32 v[184:185], v[184:185], 1.0 op_sel_hi:[1,0]
	v_pk_add_f32 v[188:189], v[188:189], 1.0 op_sel_hi:[1,0]
	v_pk_add_f32 v[186:187], v[186:187], 1.0 op_sel_hi:[1,0]
	v_pk_add_f32 v[190:191], v[190:191], 1.0 op_sel_hi:[1,0]
	v_rcp_f32_e32 v184, v184
	v_rcp_f32_e32 v188, v188
	v_rcp_f32_e32 v185, v185
	v_rcp_f32_e32 v189, v189
	v_rcp_f32_e32 v186, v186
	v_rcp_f32_e32 v190, v190
	v_rcp_f32_e32 v187, v187
	v_rcp_f32_e32 v191, v191
	v_pk_mul_f32 v[184:185], v[46:47], v[184:185]
	v_pk_mul_f32 v[188:189], v[38:39], v[188:189]
	v_pk_mul_f32 v[186:187], v[48:49], v[186:187]
	v_pk_mul_f32 v[190:191], v[40:41], v[190:191]
	v_pk_mul_f32 v[184:185], v[42:43], v[184:185]
	v_pk_mul_f32 v[188:189], v[34:35], v[188:189]
	v_pk_mul_f32 v[186:187], v[44:45], v[186:187]
	v_pk_mul_f32 v[190:191], v[36:37], v[190:191]
	v_cvt_pk_bf16_f32 v196, v184, v185
	v_cvt_pk_bf16_f32 v198, v188, v189
	v_cvt_pk_bf16_f32 v197, v186, v187
	v_cvt_pk_bf16_f32 v199, v190, v191
	s_nop 1
	v_permlane16_swap_b32_e32 v196, v198
	v_permlane16_swap_b32_e32 v197, v199
	global_store_dwordx4 v[202:203], v[196:199], off
	v_add_u32_e32 v200, 0x6e000, v0
	v_mov_b32_e32 v201, v1
	v_lshl_add_u64 v[200:201], v[200:201], 1, s[20:21]
	v_pk_mul_f32 v[184:185], v[204:205], v[30:31]
	v_pk_mul_f32 v[188:189], v[204:205], v[22:23]
	v_pk_mul_f32 v[186:187], v[204:205], v[32:33]
	v_pk_mul_f32 v[190:191], v[204:205], v[24:25]
	v_exp_f32_e32 v184, v184
	v_exp_f32_e32 v188, v188
	v_exp_f32_e32 v185, v185
	v_exp_f32_e32 v189, v189
	v_exp_f32_e32 v186, v186
	v_exp_f32_e32 v190, v190
	v_exp_f32_e32 v187, v187
	v_exp_f32_e32 v191, v191
	v_pk_add_f32 v[184:185], v[184:185], 1.0 op_sel_hi:[1,0]
	v_pk_add_f32 v[188:189], v[188:189], 1.0 op_sel_hi:[1,0]
	v_pk_add_f32 v[186:187], v[186:187], 1.0 op_sel_hi:[1,0]
	v_pk_add_f32 v[190:191], v[190:191], 1.0 op_sel_hi:[1,0]
	v_rcp_f32_e32 v184, v184
	v_rcp_f32_e32 v188, v188
	v_rcp_f32_e32 v185, v185
	v_rcp_f32_e32 v189, v189
	v_rcp_f32_e32 v186, v186
	v_rcp_f32_e32 v190, v190
	v_rcp_f32_e32 v187, v187
	v_rcp_f32_e32 v191, v191
	v_pk_mul_f32 v[184:185], v[30:31], v[184:185]
	v_pk_mul_f32 v[188:189], v[22:23], v[188:189]
	v_pk_mul_f32 v[186:187], v[32:33], v[186:187]
	v_pk_mul_f32 v[190:191], v[24:25], v[190:191]
	v_pk_mul_f32 v[184:185], v[26:27], v[184:185]
	v_pk_mul_f32 v[188:189], v[18:19], v[188:189]
	v_pk_mul_f32 v[186:187], v[28:29], v[186:187]
	v_pk_mul_f32 v[190:191], v[20:21], v[190:191]
	v_cvt_pk_bf16_f32 v192, v184, v185
	v_cvt_pk_bf16_f32 v194, v188, v189
	v_cvt_pk_bf16_f32 v193, v186, v187
	v_cvt_pk_bf16_f32 v195, v190, v191
	s_nop 1
	v_permlane16_swap_b32_e32 v192, v194
	v_permlane16_swap_b32_e32 v193, v195
	global_store_dwordx4 v[200:201], v[192:195], off
	v_add_u32_e32 v202, 0x79000, v0
	v_mov_b32_e32 v203, v1
	v_lshl_add_u64 v[202:203], v[202:203], 1, s[20:21]
	v_pk_mul_f32 v[184:185], v[204:205], v[14:15]
	v_pk_mul_f32 v[188:189], v[204:205], v[6:7]
	v_pk_mul_f32 v[186:187], v[204:205], v[16:17]
	v_pk_mul_f32 v[190:191], v[204:205], v[8:9]
	v_exp_f32_e32 v184, v184
	v_exp_f32_e32 v188, v188
	v_exp_f32_e32 v185, v185
	v_exp_f32_e32 v189, v189
	v_exp_f32_e32 v186, v186
	v_exp_f32_e32 v190, v190
	v_exp_f32_e32 v187, v187
	v_exp_f32_e32 v191, v191
	v_pk_add_f32 v[184:185], v[184:185], 1.0 op_sel_hi:[1,0]
	v_pk_add_f32 v[188:189], v[188:189], 1.0 op_sel_hi:[1,0]
	v_pk_add_f32 v[186:187], v[186:187], 1.0 op_sel_hi:[1,0]
	v_pk_add_f32 v[190:191], v[190:191], 1.0 op_sel_hi:[1,0]
	v_rcp_f32_e32 v184, v184
	v_rcp_f32_e32 v188, v188
	v_rcp_f32_e32 v185, v185
	v_rcp_f32_e32 v189, v189
	v_rcp_f32_e32 v186, v186
	v_rcp_f32_e32 v190, v190
	v_rcp_f32_e32 v187, v187
	v_rcp_f32_e32 v191, v191
	v_pk_mul_f32 v[184:185], v[14:15], v[184:185]
	v_pk_mul_f32 v[188:189], v[6:7], v[188:189]
	v_pk_mul_f32 v[186:187], v[16:17], v[186:187]
	v_pk_mul_f32 v[190:191], v[8:9], v[190:191]
	v_pk_mul_f32 v[184:185], v[10:11], v[184:185]
	v_pk_mul_f32 v[188:189], v[2:3], v[188:189]
	v_pk_mul_f32 v[186:187], v[12:13], v[186:187]
	v_pk_mul_f32 v[190:191], v[4:5], v[190:191]
	v_cvt_pk_bf16_f32 v196, v184, v185
	v_cvt_pk_bf16_f32 v198, v188, v189
	v_cvt_pk_bf16_f32 v197, v186, v187
	v_cvt_pk_bf16_f32 v199, v190, v191
	s_nop 1
	v_permlane16_swap_b32_e32 v196, v198
	v_permlane16_swap_b32_e32 v197, v199
	global_store_dwordx4 v[202:203], v[196:199], off
	s_and_b64 vcc, exec, s[8:9]
	s_mov_b64 s[22:23], s[18:19]
	s_mov_b64 s[24:25], s[16:17]
	s_mov_b32 s21, s10
	s_mov_b32 s20, s14
	s_cbranch_vccz .LBB0_261
	v_readlane_b32 s4, v241, 14
	s_waitcnt vmcnt(0)
	v_readlane_b32 s5, v241, 15
	s_andn2_b64 vcc, exec, s[4:5]
	s_mov_b32 s51, 0x80ff
	s_cbranch_vccnz .LBB0_268
	s_barrier
